# scan: next item's raw tile prefetched by LDS-DMA into the idle raw image during the first scan_dir call (strategy 7.10); tile phase only zero-fills out-of-sequence rows
# baseline (speedup 1.0000x reference)
; __device__ __forceinline__ int tid_opaque(int wv) { return wv * 64 + lane_fresh(); }
; __device__ __forceinline__ void scan_mfma(PP p, unsigned char* shm, int wv) {
;     const int tid_ = tid_opaque(wv); const int tid = tid_;
;     const int lane = tid & 63, n = wv, l31 = lane & 31, hl = lane >> 5;
;     constexpr int XS = 520;
;     bf16_t* xs = (bf16_t*)shm;
;     const bf16_t* proj = (const bf16_t*)(p->ws + WS_PROJ);
;     for (int item = blockIdx.x; item < 512 + 32; item += gridDim.x) {
;         const int id = item < 512 ? item : 512 + ((item - 512) >> 2);
;         const int quarter = item < 512 ? -1 : ((item - 512) & 3);
;         int rowbase, t0, seqlen; bool latent;
;         if (id < 512) { const int b = id >> 8, k = id & 255; t0 = 64 * k; rowbase = b * S + t0; seqlen = S; latent = true; }
;         else { const int j = id - 512, b = j >> 2, k = j & 3; t0 = 64 * k; rowbase = NLAT + b * LC + t0; seqlen = LC; latent = false; }
;         const int seqbase = rowbase - t0;
;         ScanW w0, w1;
.LBB0_327:
	s_or_b64 exec, exec, s[4:5]
	s_mov_b64 s[8:9], s[0:1]
	s_mov_b32 s27, -1
	s_mov_b32 s6, -1
	s_cmpk_gt_i32 s2, 0x21f
	s_waitcnt lgkmcnt(0)
	s_barrier
	s_cbranch_scc1 .LBB0_453
	s_load_dwordx2 s[4:5], s[8:9], 0xd0
	s_mov_b32 s17, 0
	v_mbcnt_lo_u32_b32 v0, s6, 0
	v_mbcnt_hi_u32_b32 v0, s6, v0
	v_and_b32_e32 v148, 31, v0
	s_waitcnt lgkmcnt(0)
	s_add_u32 s10, s4, 0x9c77000
	s_addc_u32 s11, s5, 0
	s_add_u32 s12, s4, 0x1c72000
	s_addc_u32 s13, s5, 0
	s_add_u32 s22, s4, 0x1600000
	s_addc_u32 s23, s5, 0
	s_lshl_b64 s[6:7], s[16:17], 13
	s_add_u32 s14, s22, s6
	s_addc_u32 s15, s23, s7
	s_add_i32 s6, s16, 8
	s_mov_b32 s7, s17
	s_lshl_b64 s[6:7], s[6:7], 13
	s_add_u32 s18, s22, s6
	s_addc_u32 s19, s23, s7
	s_add_i32 s6, s16, 16
	s_mov_b32 s7, s17
	s_add_i32 s50, s33, 0x200
	s_lshl_b64 s[6:7], s[6:7], 13
	s_add_u32 s20, s22, s6
	s_addc_u32 s21, s23, s7
	s_add_i32 s16, s16, 24
	s_lshl_b64 s[6:7], s[16:17], 13
	s_add_u32 s16, s22, s6
	s_addc_u32 s17, s23, s7
	s_lshl_b32 s6, s33, 1
	s_add_i32 s6, s6, 0
	s_add_u32 s52, s4, 0x5c77000
	s_addc_u32 s53, s5, 0
	v_lshrrev_b32_e32 v1, 5, v0
	v_bfe_u32 v0, v0, 5, 1
	s_add_u32 s54, s4, 0x165a000
	v_lshlrev_b32_e32 v149, 3, v0
	v_lshl_add_u32 v32, v0, 4, s6
	s_movk_i32 s51, 0x410
	v_mul_u32_u24_e32 v151, 0x1040, v0
	v_lshl_or_b32 v1, v1, 2, 8
	v_cmp_eq_u32_e64 s[6:7], 0, v0
	v_lshlrev_b32_e32 v153, 11, v0
	s_addc_u32 s55, s5, 0
	v_mov_b32_e32 v0, 0xffffe390
	v_mul_u32_u24_e32 v33, 0x410, v148
	v_mul_u32_u24_e32 v152, 0x410, v1
	v_lshlrev_b32_e32 v157, 9, v1
	v_mad_u32_u24 v185, v1, s51, v0
	s_add_u32 s57, s4, 0x3c77000
	v_mov_b32_e32 v1, 0
	s_addc_u32 s58, s5, 0
	v_mov_b32_e32 v2, v1
	v_mov_b32_e32 v3, v1
	v_mov_b32_e32 v4, v1
	v_mov_b32_e32 v5, v1
	v_mov_b32_e32 v6, v1
	v_mov_b32_e32 v7, v1
	v_mov_b32_e32 v8, v1
	v_mov_b32_e32 v9, v1
	v_mov_b32_e32 v10, v1
	v_mov_b32_e32 v11, v1
	v_mov_b32_e32 v12, v1
	v_mov_b32_e32 v13, v1
	v_mov_b32_e32 v14, v1
	v_mov_b32_e32 v15, v1
	v_mov_b32_e32 v16, v1
	v_mov_b32_e32 v17, v1
	v_mov_b32_e32 v18, v1
	v_mov_b32_e32 v19, v1
	v_mov_b32_e32 v20, v1
	v_mov_b32_e32 v21, v1
	v_mov_b32_e32 v22, v1
	v_mov_b32_e32 v23, v1
	v_mov_b32_e32 v24, v1
	v_mov_b32_e32 v25, v1
	v_mov_b32_e32 v26, v1
	v_mov_b32_e32 v27, v1
	v_mov_b32_e32 v28, v1
	v_mov_b32_e32 v29, v1
	v_mov_b32_e32 v30, v1
	v_mov_b32_e32 v31, v1
	v_add_u32_e32 v187, v32, v33
	v_mbcnt_lo_u32_b32 v32, -1, 0
	s_add_u32 s59, s4, 0x7c77000
	v_mov_b32_e32 v0, v1
	v_mbcnt_hi_u32_b32 v188, -1, v32
	v_mov_b64_e32 v[32:33], v[30:31]
	v_or_b32_e32 v150, s33, v148
	v_or_b32_e32 v160, 0x1600, v153
	v_or_b32_e32 v161, 0x2000, v153
	v_or_b32_e32 v162, 0x2200, v153
	v_or_b32_e32 v163, 0x2400, v153
	v_or_b32_e32 v164, 0x2600, v153
	v_or_b32_e32 v165, 0x3000, v153
	v_or_b32_e32 v166, 0x3200, v153
	v_or_b32_e32 v167, 0x3400, v153
	v_or_b32_e32 v168, 0x3600, v153
	v_or_b32_e32 v169, 0x4000, v153
	v_or_b32_e32 v170, 0x4200, v153
	v_or_b32_e32 v171, 0x4400, v153
	v_or_b32_e32 v172, 0x4600, v153
	v_or_b32_e32 v173, 0x5000, v153
	v_or_b32_e32 v174, 0x5200, v153
	v_or_b32_e32 v175, 0x5400, v153
	v_or_b32_e32 v176, 0x5600, v153
	v_or_b32_e32 v177, 0x6000, v153
	v_or_b32_e32 v178, 0x6200, v153
	v_or_b32_e32 v179, 0x6400, v153
	v_or_b32_e32 v180, 0x6600, v153
	v_or_b32_e32 v181, 0x7000, v153
	v_or_b32_e32 v182, 0x7200, v153
	v_or_b32_e32 v183, 0x7400, v153
	v_or_b32_e32 v184, 0x7600, v153
	s_addc_u32 s60, s5, 0
	s_movk_i32 s61, 0xc0
	s_movk_i32 s64, 0x100
	s_add_i32 s65, 0, 0x10400
	s_movk_i32 s66, 0x10c0
	s_movk_i32 s67, 0xe00
	s_movk_i32 s68, 0xec0
	s_movk_i32 s69, 0xcc0
	s_movk_i32 s70, 0xac0
	s_movk_i32 s71, 0x8c0
	s_movk_i32 s72, 0x6c0
	s_movk_i32 s73, 0x4c0
	s_movk_i32 s74, 0x2c0
	s_movk_i32 s75, 0x1000
	v_mov_b32_e32 v186, 0x3d2aaaab
	s_mov_b32 s76, 0xbdcccccd
	s_movk_i32 s77, 0x7fff
	s_mov_b32 s78, s2
	s_mov_b32 s97, 0
	v_mov_b64_e32 v[30:31], v[28:29]
	v_mov_b64_e32 v[28:29], v[26:27]
	v_mov_b64_e32 v[26:27], v[24:25]
	v_mov_b64_e32 v[24:25], v[22:23]
	v_mov_b64_e32 v[22:23], v[20:21]
	v_mov_b64_e32 v[20:21], v[18:19]
	v_mov_b64_e32 v[18:19], v[16:17]
	v_mov_b64_e32 v[16:17], v[14:15]
	v_mov_b64_e32 v[14:15], v[12:13]
	v_mov_b64_e32 v[12:13], v[10:11]
	v_mov_b64_e32 v[10:11], v[8:9]
	v_mov_b64_e32 v[8:9], v[6:7]
	v_mov_b64_e32 v[6:7], v[4:5]
	v_mov_b64_e32 v[4:5], v[2:3]
	v_mov_b64_e32 v[2:3], v[0:1]
	s_branch .LBB0_330

; __device__ __forceinline__ int tid_opaque(int wv) { return wv * 64 + lane_fresh(); }
; __device__ __forceinline__ void scan_mfma(PP p, unsigned char* shm, int wv) {
;     ...
;         {
;             const int tid = tid_opaque(wv);
;             bf16_t* raw = (bf16_t*)(shm + 66560);
; #pragma unroll
;             for (int i = 0; i < 9; ++i) {
;                 const int piece = tid + 512 * i;
;                 if (piece < 67 * 64) {
;                     const int row = piece >> 6, c8 = piece & 63, tt = t0 - 2 + row;
;                     u32x4 v = {0u, 0u, 0u, 0u};
;                     if (tt >= 0 && tt < seqlen) v = *(const u32x4*)(proj + (size_t)(seqbase + tt) * DIN + 8 * c8);
;                     *(u32x4*)(raw + row * 512 + 8 * c8) = v;
;                 }
;             }
.LBB0_332:
	s_add_i32 s4, s78, 0xfffffe00
	s_lshr_b32 s5, s4, 2
	s_addk_i32 s5, 0x200
	s_lshl_b32 s4, s78, 6
	s_lshl_b32 s35, s5, 6
	s_and_b32 s34, s4, 0x3fc0
	s_and_b32 s36, s35, 0xc0
	s_and_b64 s[30:31], s[22:23], exec
	s_mov_b32 s30, -1
	s_cselect_b32 s38, s34, s36
	v_mbcnt_lo_u32_b32 v0, s30, 0
	v_mbcnt_hi_u32_b32 v0, s30, v0
	v_add_u32_e32 v54, s33, v0
	v_lshlrev_b32_e32 v0, 4, v0
	s_cselect_b32 s4, s4, s35
	v_and_b32_e32 v0, 0x3f0, v0
	s_cselect_b32 s37, 0x4000, s64
	s_sub_i32 s36, s4, s38
	s_add_i32 s38, s38, -2
	v_lshl_add_u64 v[38:39], s[10:11], 0, v[0:1]
	v_add_u32_e32 v0, s65, v0
	s_mov_b64 s[30:31], exec
	s_cmp_eq_u32 s97, 1
	s_cbranch_scc0 .Lscan_pf_normal
	s_mov_b32 s97, 0
	v_mov_b32_e32 v2, 0
	v_mov_b32_e32 v3, 0
	v_mov_b32_e32 v4, 0
	v_mov_b32_e32 v5, 0
	s_lshr_b32 s99, s33, 6
	s_add_i32 s98, s38, s99
	s_lshl_b32 s99, s99, 10
	s_cmp_lt_u32 s98, s37
	s_cbranch_scc1 .Lscan_pf_z0
	v_add_u32_e32 v95, s99, v0
	ds_write_b128 v95, v[2:5]
.Lscan_pf_z0:
	s_add_i32 s98, s98, 8
	s_addk_i32 s99, 0x2000
	s_cmp_lt_u32 s98, s37
	s_cbranch_scc1 .Lscan_pf_z1
	v_add_u32_e32 v95, s99, v0
	ds_write_b128 v95, v[2:5]

; __device__ __forceinline__ int tid_opaque(int wv) { return wv * 64 + lane_fresh(); }
; __device__ __forceinline__ void scan_mfma(PP p, unsigned char* shm, int wv) {
;     ...
;         {
;             const int tid = tid_opaque(wv);
;             bf16_t* raw = (bf16_t*)(shm + 66560);
; #pragma unroll
;             for (int i = 0; i < 9; ++i) {
;                 const int piece = tid + 512 * i;
;                 if (piece < 67 * 64) {
;                     const int row = piece >> 6, c8 = piece & 63, tt = t0 - 2 + row;
;                     u32x4 v = {0u, 0u, 0u, 0u};
;                     if (tt >= 0 && tt < seqlen) v = *(const u32x4*)(proj + (size_t)(seqbase + tt) * DIN + 8 * c8);
;                     *(u32x4*)(raw + row * 512 + 8 * c8) = v;
;                 }
;             }
.Lscan_pf_z7:
	s_add_i32 s98, s98, 8
	s_addk_i32 s99, 0x2000
	s_cmp_lt_u32 s98, s37
	s_cbranch_scc1 .Lscan_pf_z8
	s_cmpk_lt_u32 s33, 0xc0
	s_cbranch_scc0 .Lscan_pf_z8
	v_add_u32_e32 v95, s99, v0
	ds_write_b128 v95, v[2:5]
.Lscan_pf_z8:
	s_waitcnt vmcnt(11)
	s_branch .LBB0_368
.Lscan_pf_normal:
	v_ashrrev_i32_e32 v95, 6, v54
	v_add_u32_e32 v96, s38, v95
	v_lshl_add_u32 v86, v95, 10, v0
	v_mov_b32_e32 v2, 0
	v_mov_b32_e32 v3, 0
	v_mov_b32_e32 v4, 0
	v_mov_b32_e32 v5, 0
	v_cmp_gt_u32_e32 vcc, s37, v96
	v_cmp_gt_i32_e64 s[34:35], s66, v54
	s_and_b64 vcc, vcc, s[34:35]
	s_and_b64 exec, s[30:31], vcc
	v_add_u32_e32 v97, s36, v96
	v_mad_i64_i32 v[98:99], s[40:41], v97, s67, v[38:39]
	global_load_dwordx4 v[2:5], v[98:99], off
	s_mov_b64 exec, s[30:31]
	v_add_u32_e32 v95, 0x200, v54
	v_ashrrev_i32_e32 v95, 6, v95
	v_add_u32_e32 v96, s38, v95
	v_lshl_add_u32 v87, v95, 10, v0
	v_mov_b32_e32 v6, 0
	v_mov_b32_e32 v7, 0
	v_mov_b32_e32 v8, 0
	v_mov_b32_e32 v9, 0
	v_cmp_gt_u32_e32 vcc, s37, v96
	v_cmp_gt_i32_e64 s[34:35], s68, v54
	s_and_b64 vcc, vcc, s[34:35]
	s_and_b64 exec, s[30:31], vcc
	v_add_u32_e32 v97, s36, v96
	v_mad_i64_i32 v[98:99], s[40:41], v97, s67, v[38:39]
	global_load_dwordx4 v[6:9], v[98:99], off
	s_mov_b64 exec, s[30:31]
	v_add_u32_e32 v95, 0x400, v54
	v_ashrrev_i32_e32 v95, 6, v95
	v_add_u32_e32 v96, s38, v95
	v_lshl_add_u32 v88, v95, 10, v0
	v_mov_b32_e32 v10, 0
	v_mov_b32_e32 v11, 0
	v_mov_b32_e32 v12, 0
	v_mov_b32_e32 v13, 0
	v_cmp_gt_u32_e32 vcc, s37, v96
	v_cmp_gt_i32_e64 s[34:35], s69, v54
	s_and_b64 vcc, vcc, s[34:35]
	s_and_b64 exec, s[30:31], vcc
	v_add_u32_e32 v97, s36, v96
	v_mad_i64_i32 v[98:99], s[40:41], v97, s67, v[38:39]
	global_load_dwordx4 v[10:13], v[98:99], off
	s_mov_b64 exec, s[30:31]
	v_add_u32_e32 v95, 0x600, v54
	v_ashrrev_i32_e32 v95, 6, v95
	v_add_u32_e32 v96, s38, v95
	v_lshl_add_u32 v89, v95, 10, v0
	v_mov_b32_e32 v14, 0
	v_mov_b32_e32 v15, 0
	v_mov_b32_e32 v16, 0
	v_mov_b32_e32 v17, 0
	v_cmp_gt_u32_e32 vcc, s37, v96
	v_cmp_gt_i32_e64 s[34:35], s70, v54
	s_and_b64 vcc, vcc, s[34:35]
	s_and_b64 exec, s[30:31], vcc
	v_add_u32_e32 v97, s36, v96
	v_mad_i64_i32 v[98:99], s[40:41], v97, s67, v[38:39]
	global_load_dwordx4 v[14:17], v[98:99], off
	s_mov_b64 exec, s[30:31]
	v_add_u32_e32 v95, 0x800, v54
	v_ashrrev_i32_e32 v95, 6, v95
	v_add_u32_e32 v96, s38, v95
	v_lshl_add_u32 v90, v95, 10, v0
	v_mov_b32_e32 v18, 0
	v_mov_b32_e32 v19, 0
	v_mov_b32_e32 v20, 0
	v_mov_b32_e32 v21, 0
	v_cmp_gt_u32_e32 vcc, s37, v96
	v_cmp_gt_i32_e64 s[34:35], s71, v54
	s_and_b64 vcc, vcc, s[34:35]
	s_and_b64 exec, s[30:31], vcc
	v_add_u32_e32 v97, s36, v96
	v_mad_i64_i32 v[98:99], s[40:41], v97, s67, v[38:39]
	global_load_dwordx4 v[18:21], v[98:99], off
	s_mov_b64 exec, s[30:31]
	v_add_u32_e32 v95, 0xa00, v54
	v_ashrrev_i32_e32 v95, 6, v95
	v_add_u32_e32 v96, s38, v95
	v_lshl_add_u32 v91, v95, 10, v0
	v_mov_b32_e32 v22, 0
	v_mov_b32_e32 v23, 0
	v_mov_b32_e32 v24, 0
	v_mov_b32_e32 v25, 0
	v_cmp_gt_u32_e32 vcc, s37, v96
	v_cmp_gt_i32_e64 s[34:35], s72, v54
	s_and_b64 vcc, vcc, s[34:35]
	s_and_b64 exec, s[30:31], vcc
	v_add_u32_e32 v97, s36, v96
	v_mad_i64_i32 v[98:99], s[40:41], v97, s67, v[38:39]
	global_load_dwordx4 v[22:25], v[98:99], off
	s_mov_b64 exec, s[30:31]
	v_add_u32_e32 v95, 0xc00, v54
	v_ashrrev_i32_e32 v95, 6, v95
	v_add_u32_e32 v96, s38, v95
	v_lshl_add_u32 v92, v95, 10, v0
	v_mov_b32_e32 v26, 0
	v_mov_b32_e32 v27, 0
	v_mov_b32_e32 v28, 0
	v_mov_b32_e32 v29, 0
	v_cmp_gt_u32_e32 vcc, s37, v96
	v_cmp_gt_i32_e64 s[34:35], s73, v54
	s_and_b64 vcc, vcc, s[34:35]
	s_and_b64 exec, s[30:31], vcc
	v_add_u32_e32 v97, s36, v96
	v_mad_i64_i32 v[98:99], s[40:41], v97, s67, v[38:39]
	global_load_dwordx4 v[26:29], v[98:99], off
	s_mov_b64 exec, s[30:31]
	v_add_u32_e32 v95, 0xe00, v54
	v_ashrrev_i32_e32 v95, 6, v95
	v_add_u32_e32 v96, s38, v95
	v_lshl_add_u32 v93, v95, 10, v0
	v_mov_b32_e32 v30, 0
	v_mov_b32_e32 v31, 0
	v_mov_b32_e32 v32, 0
	v_mov_b32_e32 v33, 0
	v_cmp_gt_u32_e32 vcc, s37, v96
	v_cmp_gt_i32_e64 s[34:35], s74, v54
	s_and_b64 vcc, vcc, s[34:35]
	s_and_b64 exec, s[30:31], vcc
	v_add_u32_e32 v97, s36, v96
	v_mad_i64_i32 v[98:99], s[40:41], v97, s67, v[38:39]
	global_load_dwordx4 v[30:33], v[98:99], off
	s_mov_b64 exec, s[30:31]
	v_add_u32_e32 v95, 0x1000, v54
	v_ashrrev_i32_e32 v95, 6, v95
	v_add_u32_e32 v96, s38, v95
	v_lshl_add_u32 v94, v95, 10, v0
	v_mov_b32_e32 v82, 0
	v_mov_b32_e32 v83, 0
	v_mov_b32_e32 v84, 0
	v_mov_b32_e32 v85, 0
	v_cmp_gt_u32_e32 vcc, s37, v96
	v_cmp_gt_i32_e64 s[34:35], s61, v54
	s_and_b64 vcc, vcc, s[34:35]
	s_and_b64 exec, s[30:31], vcc
	v_add_u32_e32 v97, s36, v96
	v_mad_i64_i32 v[98:99], s[40:41], v97, s67, v[38:39]
	global_load_dwordx4 v[82:85], v[98:99], off
	s_mov_b64 exec, s[30:31]
	s_waitcnt vmcnt(0)
	v_cmp_gt_i32_e32 vcc, s66, v54
	s_and_b64 exec, s[30:31], vcc
	ds_write_b128 v86, v[2:5]
	v_cmp_gt_i32_e32 vcc, s68, v54
	s_and_b64 exec, s[30:31], vcc
	ds_write_b128 v87, v[6:9]
	v_cmp_gt_i32_e32 vcc, s69, v54
	s_and_b64 exec, s[30:31], vcc
	ds_write_b128 v88, v[10:13]
	v_cmp_gt_i32_e32 vcc, s70, v54
	s_and_b64 exec, s[30:31], vcc
	ds_write_b128 v89, v[14:17]
	v_cmp_gt_i32_e32 vcc, s71, v54
	s_and_b64 exec, s[30:31], vcc
	ds_write_b128 v90, v[18:21]
	v_cmp_gt_i32_e32 vcc, s72, v54
	s_and_b64 exec, s[30:31], vcc
	ds_write_b128 v91, v[22:25]
	v_cmp_gt_i32_e32 vcc, s73, v54
	s_and_b64 exec, s[30:31], vcc
	ds_write_b128 v92, v[26:29]
	v_cmp_gt_i32_e32 vcc, s74, v54
	s_and_b64 exec, s[30:31], vcc
	ds_write_b128 v93, v[30:33]
	v_cmp_gt_i32_e32 vcc, s61, v54
	s_and_b64 exec, s[30:31], vcc
	ds_write_b128 v94, v[82:85]
	s_mov_b64 exec, s[30:31]
; __device__ __forceinline__ unsigned pk2(float lo, float hi) { unsigned r; asm("v_cvt_pk_bf16_f32 %0, %1, %2" : "=v"(r) : "v"(lo), "v"(hi)); return r; }
; __device__ __forceinline__ float bflo(unsigned w) { return __uint_as_float(w << 16); }
; __device__ __forceinline__ float bfhi(unsigned w) { return __uint_as_float(w & 0xFFFF0000u); }
; __device__ __forceinline__ void scan_loadw(PP p, int dir, int n, int ct, int l31, int hl, ScanW& w) {
;     ...
;     w.sp8l2 = ((const float*)(p->ws + WS_SP8))[ch] * 1.4426950408889634f;
; __device__ __forceinline__ void scan_mfma(PP p, unsigned char* shm, int wv) {
;     ...
;             __syncthreads();
;             const int cq = tid & 127, tq = tid >> 7, c4 = 4 * cq;
;             const f32x4 k0 = *(const f32x4*)(p->rnn_conv_w + c4), k1 = *(const f32x4*)(p->rnn_conv_w + 512 + c4), k2 = *(const f32x4*)(p->rnn_conv_w + 1024 + c4),
;                         k3 = *(const f32x4*)(p->rnn_conv_w + 1536 + c4), kb = *(const f32x4*)(p->rnn_conv_b + c4);
;             auto ld4 = [&](int row) -> f32x4 { const u32x2 w = *(const u32x2*)(raw + row * 512 + c4); f32x4 r; r[0] = bflo(w.x); r[1] = bfhi(w.x); r[2] = bflo(w.y); r[3] = bfhi(w.y); return r; };
;             f32x4 xm2 = ld4(16 * tq), xm1 = ld4(16 * tq + 1), x0 = ld4(16 * tq + 2);
; #pragma unroll
;             for (int t = 0; t < 16; ++t) {
;                 const f32x4 xp1 = ld4(16 * tq + t + 3);
;                 const f32x4 o = kb + k0 * xm2 + k1 * xm1 + k2 * x0 + k3 * xp1;
;                 u32x2 w; w.x = pk2(o[0], o[1]); w.y = pk2(o[2], o[3]);
;                 *(u32x2*)(xs + (16 * tq + t) * XS + c4) = w;
;                 xm2 = xm1; xm1 = x0; x0 = xp1;
;             }
.LBB0_368:
	s_or_b64 exec, exec, s[30:31]
	s_waitcnt lgkmcnt(0)
	s_barrier
	s_load_dwordx4 s[36:39], s[8:9], 0x40
	v_lshlrev_b32_e32 v0, 2, v54
	v_and_b32_e32 v55, 0x1fc, v0
	v_lshlrev_b32_e32 v0, 2, v55
	s_waitcnt lgkmcnt(0)
	global_load_dwordx4 v[34:37], v0, s[36:37]
	global_load_dwordx4 v[46:49], v0, s[38:39]
	v_lshl_add_u64 v[38:39], s[36:37], 0, v[0:1]
	global_load_dwordx4 v[42:45], v0, s[36:37] offset:2048
	v_add_co_u32_e32 v38, vcc, s75, v38
	v_ashrrev_i32_e32 v56, 3, v54
	s_nop 0
	v_addc_co_u32_e32 v39, vcc, 0, v39, vcc
	global_load_dwordx4 v[50:53], v[38:39], off
	s_nop 0
	global_load_dwordx4 v[38:41], v[38:39], off offset:2048
	v_and_b32_e32 v54, -16, v56
	v_lshlrev_b32_e32 v0, 1, v55
	v_lshlrev_b32_e32 v55, 10, v54
	v_add3_u32 v57, s65, v55, v0
	ds_read2st64_b64 v[58:61], v57 offset1:2
	v_add_u32_e32 v156, s65, v0
	v_add_u32_e32 v158, v156, v55
	ds_read_b64 v[62:63], v57 offset:2048
	ds_read_b64 v[64:65], v158 offset:3072
	v_add_u32_e32 v0, 0, v0
	s_waitcnt lgkmcnt(2)
	v_lshlrev_b32_e32 v66, 16, v58
	v_and_b32_e32 v67, 0xffff0000, v58
	v_lshlrev_b32_e32 v58, 16, v59
	v_and_b32_e32 v59, 0xffff0000, v59
	v_lshlrev_b32_e32 v68, 16, v60
	v_and_b32_e32 v69, 0xffff0000, v60
	v_lshlrev_b32_e32 v60, 16, v61
	v_and_b32_e32 v61, 0xffff0000, v61
	s_waitcnt lgkmcnt(1)
	v_lshlrev_b32_e32 v70, 16, v62
	v_and_b32_e32 v71, 0xffff0000, v62
	v_lshlrev_b32_e32 v62, 16, v63
	v_and_b32_e32 v63, 0xffff0000, v63
	s_waitcnt lgkmcnt(0)
	v_lshlrev_b32_e32 v72, 16, v64
	v_and_b32_e32 v73, 0xffff0000, v64
	v_mad_u64_u32 v[54:55], s[30:31], v54, s51, v[0:1]
	v_lshlrev_b32_e32 v64, 16, v65
	v_and_b32_e32 v65, 0xffff0000, v65
	s_and_b64 s[30:31], s[22:23], exec
	s_cselect_b32 s34, s78, s5
	s_and_b32 s5, s78, 3
	s_and_b64 s[30:31], s[22:23], exec
	s_cselect_b32 s79, -1, s5
	s_ashr_i32 s5, s4, 31
	s_lshl_b64 s[4:5], s[4:5], 10
	s_mov_b32 s80, 0
	s_mov_b64 s[44:45], -1
	s_waitcnt vmcnt(3)
	v_pk_fma_f32 v[66:67], v[34:35], v[66:67], v[46:47]
	v_pk_fma_f32 v[58:59], v[36:37], v[58:59], v[48:49]
	v_pk_fma_f32 v[76:77], v[36:37], v[60:61], v[48:49]
	s_waitcnt vmcnt(2)
	v_pk_fma_f32 v[58:59], v[44:45], v[60:61], v[58:59]
	v_pk_fma_f32 v[60:61], v[42:43], v[68:69], v[66:67]
	v_pk_fma_f32 v[74:75], v[34:35], v[68:69], v[46:47]
	v_pk_fma_f32 v[78:79], v[36:37], v[62:63], v[48:49]
	s_waitcnt vmcnt(1)
	v_pk_fma_f32 v[60:61], v[50:51], v[70:71], v[60:61]
	v_pk_fma_f32 v[58:59], v[52:53], v[62:63], v[58:59]
	s_waitcnt vmcnt(0)
	s_cmp_lg_u64 s[22:23], 0
	s_cbranch_scc0 .Lscan_nomul0
	v_mul_f32_e32 v194, 0x3fb8aa3b, v100
.Lscan_nomul0:
	v_pk_fma_f32 v[60:61], v[38:39], v[72:73], v[60:61]
	v_pk_fma_f32 v[58:59], v[40:41], v[64:65], v[58:59]
	v_cvt_pk_bf16_f32 v60, v60, v61
	v_pk_fma_f32 v[66:67], v[44:45], v[62:63], v[76:77]
	v_cvt_pk_bf16_f32 v61, v58, v59
	ds_write_b64 v54, v[60:61]
	ds_read_b64 v[58:59], v158 offset:4096
	v_pk_fma_f32 v[68:69], v[42:43], v[70:71], v[74:75]
	v_pk_fma_f32 v[146:147], v[36:37], v[64:65], v[48:49]
	v_pk_fma_f32 v[62:63], v[44:45], v[64:65], v[78:79]
	v_pk_fma_f32 v[68:69], v[50:51], v[72:73], v[68:69]
	v_pk_fma_f32 v[64:65], v[52:53], v[64:65], v[66:67]
	s_waitcnt lgkmcnt(0)
	v_lshlrev_b32_e32 v66, 16, v58
	v_and_b32_e32 v67, 0xffff0000, v58
	v_lshlrev_b32_e32 v58, 16, v59
	v_and_b32_e32 v59, 0xffff0000, v59
	v_pk_fma_f32 v[68:69], v[38:39], v[66:67], v[68:69]
	v_pk_fma_f32 v[64:65], v[40:41], v[58:59], v[64:65]
	v_cvt_pk_bf16_f32 v68, v68, v69
	v_pk_fma_f32 v[80:81], v[34:35], v[70:71], v[46:47]
	v_cvt_pk_bf16_f32 v69, v64, v65
	ds_write_b64 v54, v[68:69] offset:1040
	ds_read_b64 v[64:65], v158 offset:5120
	v_pk_fma_f32 v[60:61], v[42:43], v[72:73], v[80:81]
	v_pk_fma_f32 v[154:155], v[34:35], v[72:73], v[46:47]
	v_pk_fma_f32 v[60:61], v[50:51], v[66:67], v[60:61]
	v_pk_fma_f32 v[62:63], v[52:53], v[58:59], v[62:63]
	s_waitcnt lgkmcnt(0)
	v_lshlrev_b32_e32 v72, 16, v64
	v_and_b32_e32 v73, 0xffff0000, v64
	v_lshlrev_b32_e32 v64, 16, v65
	v_and_b32_e32 v65, 0xffff0000, v65
	v_pk_fma_f32 v[60:61], v[38:39], v[72:73], v[60:61]
	v_pk_fma_f32 v[62:63], v[40:41], v[64:65], v[62:63]
	v_cvt_pk_bf16_f32 v60, v60, v61
	v_pk_fma_f32 v[68:69], v[44:45], v[58:59], v[146:147]
	v_cvt_pk_bf16_f32 v61, v62, v63
	ds_write_b64 v54, v[60:61] offset:2080
	ds_read_b64 v[60:61], v158 offset:6144
	v_pk_fma_f32 v[70:71], v[42:43], v[66:67], v[154:155]
	v_pk_fma_f32 v[62:63], v[52:53], v[64:65], v[68:69]
	v_pk_fma_f32 v[68:69], v[50:51], v[72:73], v[70:71]
	v_pk_fma_f32 v[66:67], v[34:35], v[66:67], v[46:47]
	s_waitcnt lgkmcnt(0)
	v_lshlrev_b32_e32 v70, 16, v60
	v_and_b32_e32 v71, 0xffff0000, v60
	v_lshlrev_b32_e32 v60, 16, v61
	v_and_b32_e32 v61, 0xffff0000, v61
	v_pk_fma_f32 v[68:69], v[38:39], v[70:71], v[68:69]
	v_pk_fma_f32 v[62:63], v[40:41], v[60:61], v[62:63]
	v_cvt_pk_bf16_f32 v68, v68, v69
	v_pk_fma_f32 v[58:59], v[36:37], v[58:59], v[48:49]
	v_cvt_pk_bf16_f32 v69, v62, v63
	ds_write_b64 v54, v[68:69] offset:3120
	ds_read_b64 v[62:63], v158 offset:7168
	v_pk_fma_f32 v[66:67], v[42:43], v[72:73], v[66:67]
	v_pk_fma_f32 v[58:59], v[44:45], v[64:65], v[58:59]
	v_pk_fma_f32 v[68:69], v[34:35], v[72:73], v[46:47]
	v_pk_fma_f32 v[66:67], v[50:51], v[70:71], v[66:67]
	s_waitcnt lgkmcnt(0)
	v_lshlrev_b32_e32 v72, 16, v62
	v_and_b32_e32 v73, 0xffff0000, v62
	v_pk_fma_f32 v[58:59], v[52:53], v[60:61], v[58:59]
	v_lshlrev_b32_e32 v62, 16, v63
	v_and_b32_e32 v63, 0xffff0000, v63
	v_pk_fma_f32 v[66:67], v[38:39], v[72:73], v[66:67]
	v_pk_fma_f32 v[58:59], v[40:41], v[62:63], v[58:59]
	v_cvt_pk_bf16_f32 v66, v66, v67
	v_pk_fma_f32 v[64:65], v[36:37], v[64:65], v[48:49]
	v_cvt_pk_bf16_f32 v67, v58, v59
	ds_write_b64 v54, v[66:67] offset:4160
	ds_read_b64 v[58:59], v158 offset:8192
	v_pk_fma_f32 v[66:67], v[42:43], v[70:71], v[68:69]
	v_pk_fma_f32 v[64:65], v[44:45], v[60:61], v[64:65]
	v_pk_fma_f32 v[66:67], v[50:51], v[72:73], v[66:67]
	v_pk_fma_f32 v[64:65], v[52:53], v[62:63], v[64:65]
	s_waitcnt lgkmcnt(0)
; __device__ __forceinline__ unsigned pk2(float lo, float hi) { unsigned r; asm("v_cvt_pk_bf16_f32 %0, %1, %2" : "=v"(r) : "v"(lo), "v"(hi)); return r; }
; __device__ __forceinline__ void scan_mfma(PP p, unsigned char* shm, int wv) {
;     ...
;             f32x4 xm2 = ld4(16 * tq), xm1 = ld4(16 * tq + 1), x0 = ld4(16 * tq + 2);
; #pragma unroll
;             for (int t = 0; t < 16; ++t) {
;                 const f32x4 xp1 = ld4(16 * tq + t + 3);
;                 const f32x4 o = kb + k0 * xm2 + k1 * xm1 + k2 * x0 + k3 * xp1;
;                 u32x2 w; w.x = pk2(o[0], o[1]); w.y = pk2(o[2], o[3]);
;                 *(u32x2*)(xs + (16 * tq + t) * XS + c4) = w;
;                 xm2 = xm1; xm1 = x0; x0 = xp1;
;             }
	v_lshlrev_b32_e32 v68, 16, v58
	v_and_b32_e32 v69, 0xffff0000, v58
	v_lshlrev_b32_e32 v58, 16, v59
	v_and_b32_e32 v59, 0xffff0000, v59
	v_pk_fma_f32 v[66:67], v[38:39], v[68:69], v[66:67]
	v_pk_fma_f32 v[64:65], v[40:41], v[58:59], v[64:65]
	v_cvt_pk_bf16_f32 v66, v66, v67
	v_pk_fma_f32 v[70:71], v[34:35], v[70:71], v[46:47]
	v_cvt_pk_bf16_f32 v67, v64, v65
	ds_write_b64 v54, v[66:67] offset:5200
	ds_read_b64 v[64:65], v158 offset:9216
	v_pk_fma_f32 v[60:61], v[36:37], v[60:61], v[48:49]
	v_pk_fma_f32 v[70:71], v[42:43], v[72:73], v[70:71]
	v_pk_fma_f32 v[60:61], v[44:45], v[62:63], v[60:61]
	v_pk_fma_f32 v[70:71], v[50:51], v[68:69], v[70:71]
	s_waitcnt lgkmcnt(0)
	v_lshlrev_b32_e32 v66, 16, v64
	v_and_b32_e32 v67, 0xffff0000, v64
	v_lshlrev_b32_e32 v64, 16, v65
	v_and_b32_e32 v65, 0xffff0000, v65
	v_pk_fma_f32 v[60:61], v[52:53], v[58:59], v[60:61]
	v_pk_fma_f32 v[70:71], v[38:39], v[66:67], v[70:71]
	v_pk_fma_f32 v[60:61], v[40:41], v[64:65], v[60:61]
	v_cvt_pk_bf16_f32 v70, v70, v71
	v_pk_fma_f32 v[72:73], v[34:35], v[72:73], v[46:47]
	v_cvt_pk_bf16_f32 v71, v60, v61
	ds_write_b64 v54, v[70:71] offset:6240
	ds_read_b64 v[60:61], v158 offset:10240
	v_pk_fma_f32 v[62:63], v[36:37], v[62:63], v[48:49]
	v_pk_fma_f32 v[72:73], v[42:43], v[68:69], v[72:73]
	v_pk_fma_f32 v[62:63], v[44:45], v[58:59], v[62:63]
	v_pk_fma_f32 v[72:73], v[50:51], v[66:67], v[72:73]
	s_waitcnt lgkmcnt(0)
	v_lshlrev_b32_e32 v70, 16, v60
	v_and_b32_e32 v71, 0xffff0000, v60
	v_lshlrev_b32_e32 v60, 16, v61
	v_and_b32_e32 v61, 0xffff0000, v61
	v_pk_fma_f32 v[62:63], v[52:53], v[64:65], v[62:63]
	v_pk_fma_f32 v[72:73], v[38:39], v[70:71], v[72:73]
	v_pk_fma_f32 v[62:63], v[40:41], v[60:61], v[62:63]
	v_cvt_pk_bf16_f32 v72, v72, v73
	v_pk_fma_f32 v[68:69], v[34:35], v[68:69], v[46:47]
	v_cvt_pk_bf16_f32 v73, v62, v63
	ds_write_b64 v54, v[72:73] offset:7280
	ds_read_b64 v[62:63], v158 offset:11264
	v_pk_fma_f32 v[58:59], v[36:37], v[58:59], v[48:49]
	v_pk_fma_f32 v[68:69], v[42:43], v[66:67], v[68:69]
	v_pk_fma_f32 v[58:59], v[44:45], v[64:65], v[58:59]
	v_pk_fma_f32 v[68:69], v[50:51], v[70:71], v[68:69]
	s_waitcnt lgkmcnt(0)
	v_lshlrev_b32_e32 v72, 16, v62
	v_and_b32_e32 v73, 0xffff0000, v62
	v_lshlrev_b32_e32 v62, 16, v63
	v_and_b32_e32 v63, 0xffff0000, v63
	v_pk_fma_f32 v[58:59], v[52:53], v[60:61], v[58:59]
	v_pk_fma_f32 v[68:69], v[38:39], v[72:73], v[68:69]
	v_pk_fma_f32 v[58:59], v[40:41], v[62:63], v[58:59]
	v_cvt_pk_bf16_f32 v68, v68, v69
	v_pk_fma_f32 v[66:67], v[34:35], v[66:67], v[46:47]
	v_cvt_pk_bf16_f32 v69, v58, v59
	ds_write_b64 v54, v[68:69] offset:8320
	ds_read_b64 v[58:59], v158 offset:12288
	v_pk_fma_f32 v[64:65], v[36:37], v[64:65], v[48:49]
	v_pk_fma_f32 v[66:67], v[42:43], v[70:71], v[66:67]
	v_pk_fma_f32 v[64:65], v[44:45], v[60:61], v[64:65]
	v_pk_fma_f32 v[66:67], v[50:51], v[72:73], v[66:67]
	s_waitcnt lgkmcnt(0)
	v_lshlrev_b32_e32 v68, 16, v58
	v_and_b32_e32 v69, 0xffff0000, v58
	v_lshlrev_b32_e32 v58, 16, v59
	v_and_b32_e32 v59, 0xffff0000, v59
	v_pk_fma_f32 v[64:65], v[52:53], v[62:63], v[64:65]
	v_pk_fma_f32 v[66:67], v[38:39], v[68:69], v[66:67]
	v_pk_fma_f32 v[64:65], v[40:41], v[58:59], v[64:65]
	v_cvt_pk_bf16_f32 v66, v66, v67
	v_pk_fma_f32 v[70:71], v[34:35], v[70:71], v[46:47]
	v_cvt_pk_bf16_f32 v67, v64, v65
	ds_write_b64 v54, v[66:67] offset:9360
	ds_read_b64 v[64:65], v158 offset:13312
	v_pk_fma_f32 v[60:61], v[36:37], v[60:61], v[48:49]
	v_pk_fma_f32 v[70:71], v[42:43], v[72:73], v[70:71]
	v_pk_fma_f32 v[60:61], v[44:45], v[62:63], v[60:61]
	v_pk_fma_f32 v[70:71], v[50:51], v[68:69], v[70:71]
	s_waitcnt lgkmcnt(0)
	v_lshlrev_b32_e32 v66, 16, v64
	v_and_b32_e32 v67, 0xffff0000, v64
	v_lshlrev_b32_e32 v64, 16, v65
	v_and_b32_e32 v65, 0xffff0000, v65
	v_pk_fma_f32 v[60:61], v[52:53], v[58:59], v[60:61]
	v_pk_fma_f32 v[70:71], v[38:39], v[66:67], v[70:71]
	v_pk_fma_f32 v[60:61], v[40:41], v[64:65], v[60:61]
	v_cvt_pk_bf16_f32 v70, v70, v71
	v_pk_fma_f32 v[72:73], v[34:35], v[72:73], v[46:47]
	v_cvt_pk_bf16_f32 v71, v60, v61
	ds_write_b64 v54, v[70:71] offset:10400
	ds_read_b64 v[60:61], v158 offset:14336
	v_pk_fma_f32 v[62:63], v[36:37], v[62:63], v[48:49]
	v_pk_fma_f32 v[72:73], v[42:43], v[68:69], v[72:73]
	v_pk_fma_f32 v[62:63], v[44:45], v[58:59], v[62:63]
	v_pk_fma_f32 v[72:73], v[50:51], v[66:67], v[72:73]
	s_waitcnt lgkmcnt(0)
; __device__ __forceinline__ unsigned pk2(float lo, float hi) { unsigned r; asm("v_cvt_pk_bf16_f32 %0, %1, %2" : "=v"(r) : "v"(lo), "v"(hi)); return r; }
; __device__ __forceinline__ void scan_mfma(PP p, unsigned char* shm, int wv) {
;     ...
;             f32x4 xm2 = ld4(16 * tq), xm1 = ld4(16 * tq + 1), x0 = ld4(16 * tq + 2);
; #pragma unroll
;             for (int t = 0; t < 16; ++t) {
;                 const f32x4 xp1 = ld4(16 * tq + t + 3);
;                 const f32x4 o = kb + k0 * xm2 + k1 * xm1 + k2 * x0 + k3 * xp1;
;                 u32x2 w; w.x = pk2(o[0], o[1]); w.y = pk2(o[2], o[3]);
;                 *(u32x2*)(xs + (16 * tq + t) * XS + c4) = w;
;                 xm2 = xm1; xm1 = x0; x0 = xp1;
;             }
;         }
;         __syncthreads();
	v_lshlrev_b32_e32 v70, 16, v60
	v_and_b32_e32 v71, 0xffff0000, v60
	v_lshlrev_b32_e32 v60, 16, v61
	v_and_b32_e32 v61, 0xffff0000, v61
	v_pk_fma_f32 v[62:63], v[52:53], v[64:65], v[62:63]
	v_pk_fma_f32 v[72:73], v[38:39], v[70:71], v[72:73]
	v_pk_fma_f32 v[62:63], v[40:41], v[60:61], v[62:63]
	v_cvt_pk_bf16_f32 v72, v72, v73
	v_pk_fma_f32 v[68:69], v[34:35], v[68:69], v[46:47]
	v_cvt_pk_bf16_f32 v73, v62, v63
	ds_write_b64 v54, v[72:73] offset:11440
	ds_read_b64 v[62:63], v158 offset:15360
	v_pk_fma_f32 v[58:59], v[36:37], v[58:59], v[48:49]
	v_pk_fma_f32 v[68:69], v[42:43], v[66:67], v[68:69]
	v_pk_fma_f32 v[58:59], v[44:45], v[64:65], v[58:59]
	v_pk_fma_f32 v[68:69], v[50:51], v[70:71], v[68:69]
	s_waitcnt lgkmcnt(0)
	v_lshlrev_b32_e32 v72, 16, v62
	v_and_b32_e32 v73, 0xffff0000, v62
	v_lshlrev_b32_e32 v62, 16, v63
	v_and_b32_e32 v63, 0xffff0000, v63
	v_pk_fma_f32 v[58:59], v[52:53], v[60:61], v[58:59]
	v_pk_fma_f32 v[68:69], v[38:39], v[72:73], v[68:69]
	v_pk_fma_f32 v[58:59], v[40:41], v[62:63], v[58:59]
	v_cvt_pk_bf16_f32 v68, v68, v69
	v_pk_fma_f32 v[66:67], v[34:35], v[66:67], v[46:47]
	v_cvt_pk_bf16_f32 v69, v58, v59
	ds_write_b64 v54, v[68:69] offset:12480
	ds_read_b64 v[58:59], v158 offset:16384
	v_pk_fma_f32 v[64:65], v[36:37], v[64:65], v[48:49]
	v_pk_fma_f32 v[66:67], v[42:43], v[70:71], v[66:67]
	v_pk_fma_f32 v[64:65], v[44:45], v[60:61], v[64:65]
	v_pk_fma_f32 v[66:67], v[50:51], v[72:73], v[66:67]
	s_waitcnt lgkmcnt(0)
	v_lshlrev_b32_e32 v68, 16, v58
	v_and_b32_e32 v69, 0xffff0000, v58
	v_lshlrev_b32_e32 v58, 16, v59
	v_and_b32_e32 v59, 0xffff0000, v59
	v_pk_fma_f32 v[64:65], v[52:53], v[62:63], v[64:65]
	v_pk_fma_f32 v[66:67], v[38:39], v[68:69], v[66:67]
	v_pk_fma_f32 v[64:65], v[40:41], v[58:59], v[64:65]
	v_cvt_pk_bf16_f32 v66, v66, v67
	v_pk_fma_f32 v[60:61], v[36:37], v[60:61], v[48:49]
	v_cvt_pk_bf16_f32 v67, v64, v65
	ds_write_b64 v54, v[66:67] offset:13520
	ds_read_b64 v[64:65], v158 offset:17408
	v_pk_fma_f32 v[70:71], v[34:35], v[70:71], v[46:47]
	v_pk_fma_f32 v[60:61], v[44:45], v[62:63], v[60:61]
	v_pk_fma_f32 v[70:71], v[42:43], v[72:73], v[70:71]
	v_pk_fma_f32 v[60:61], v[52:53], v[58:59], v[60:61]
	s_waitcnt lgkmcnt(0)
	v_lshlrev_b32_e32 v66, 16, v64
	v_and_b32_e32 v67, 0xffff0000, v64
	v_lshlrev_b32_e32 v64, 16, v65
	v_and_b32_e32 v65, 0xffff0000, v65
	v_pk_fma_f32 v[70:71], v[50:51], v[68:69], v[70:71]
	v_pk_fma_f32 v[60:61], v[40:41], v[64:65], v[60:61]
	v_pk_fma_f32 v[70:71], v[38:39], v[66:67], v[70:71]
	v_pk_fma_f32 v[36:37], v[36:37], v[62:63], v[48:49]
	v_cvt_pk_bf16_f32 v70, v70, v71
	v_cvt_pk_bf16_f32 v71, v60, v61
	v_or_b32_e32 v60, 15, v56
	ds_write_b64 v54, v[70:71] offset:14560
	v_lshl_add_u32 v54, v60, 10, v156
	ds_read_b64 v[54:55], v54 offset:3072
	v_pk_fma_f32 v[34:35], v[34:35], v[72:73], v[46:47]
	v_pk_fma_f32 v[36:37], v[44:45], v[58:59], v[36:37]
	v_pk_fma_f32 v[34:35], v[42:43], v[68:69], v[34:35]
	v_pk_fma_f32 v[36:37], v[52:53], v[64:65], v[36:37]
	s_waitcnt lgkmcnt(0)
	v_lshlrev_b32_e32 v56, 16, v54
	v_and_b32_e32 v57, 0xffff0000, v54
	v_lshlrev_b32_e32 v54, 16, v55
	v_and_b32_e32 v55, 0xffff0000, v55
	v_pk_fma_f32 v[34:35], v[50:51], v[66:67], v[34:35]
	v_pk_fma_f32 v[36:37], v[40:41], v[54:55], v[36:37]
	v_pk_fma_f32 v[34:35], v[38:39], v[56:57], v[34:35]
	s_nop 0
	v_cvt_pk_bf16_f32 v34, v34, v35
	v_cvt_pk_bf16_f32 v35, v36, v37
	v_mad_u64_u32 v[36:37], s[30:31], v60, s51, v[0:1]
	s_add_u32 s30, s52, s4
	s_addc_u32 s31, s53, s5
	s_ashr_i32 s35, s34, 31
	s_lshl_b64 s[34:35], s[34:35], 12
	s_add_u32 s34, s54, s34
	s_addc_u32 s35, s55, s35
	s_add_u32 s36, s57, s4
	s_addc_u32 s37, s58, s5
	s_add_u32 s38, s59, s4
	s_addc_u32 s39, s60, s5
	s_add_u32 s40, s34, 0x208000
	s_addc_u32 s41, s35, 0
	ds_write_b64 v36, v[34:35]
	s_waitcnt lgkmcnt(0)
	s_barrier
	s_branch .LBB0_371

; __device__ __forceinline__ float bf2f(bf16_t b) { return __uint_as_float(((unsigned)b) << 16); }
; __device__ __forceinline__ float fast_sigmoid(float x) { return __builtin_amdgcn_rcpf(1.0f + __builtin_amdgcn_exp2f(-1.4426950408889634f * x)); }
; template <int DIR>
; __device__ __forceinline__ void scan_dir(PP p, const bf16_t* xs, const ScanW& w, ScanW& wn, int ndir, int nct, bool do_next, int n, int ct, int l31, int hl, int id, int rowbase, bool latent, float (&hf)[2][16]) {
;     ...
;         bf16x8 af[4];
; #pragma unroll
;         for (int st = 0; st < 4; ++st) af[st] = *(const bf16x8*)(xs + (32 * rt + l31) * XS + 64 * n + 16 * st + 8 * hl);
;         f32x16 ga, gi;
; #pragma unroll
;         for (int i = 0; i < 16; ++i) { ga[i] = 0.f; gi[i] = 0.f; }
; #pragma unroll
;         for (int st = 0; st < 4; ++st) { ga = __builtin_amdgcn_mfma_f32_32x32x16_bf16(af[st], wfa[st], ga, 0, 0, 0); gi = __builtin_amdgcn_mfma_f32_32x32x16_bf16(af[st], wfi[st], gi, 0, 0, 0); }
; #pragma unroll
;         for (int i = 0; i < 16; ++i) {
;             const int token = 32 * rt + 8 * (i >> 2) + 4 * hl + (i & 3);
;             const float xv = bf2f(xs[token * XS + ch]);
;             const float rr = fast_sigmoid(ga[i] + ba), ii = fast_sigmoid(gi[i] + bi);
; __device__ __forceinline__ void scan_mfma(PP p, unsigned char* shm, int wv) {
;     ...
;             bf16_t* raw = (bf16_t*)(shm + 66560);
; #pragma unroll
;             for (int i = 0; i < 9; ++i) {
;                 const int piece = tid + 512 * i;
;                 if (piece < 67 * 64) {
;                     const int row = piece >> 6, c8 = piece & 63, tt = t0 - 2 + row;
;                     u32x4 v = {0u, 0u, 0u, 0u};
;                     if (tt >= 0 && tt < seqlen) v = *(const u32x4*)(proj + (size_t)(seqbase + tt) * DIN + 8 * c8);
;                     *(u32x4*)(raw + row * 512 + 8 * c8) = v;
;                 }
;             }
.LBB0_378:
	ds_read_b128 v[2:5], v187
	s_lshl_b32 s48, s80, 5
	v_or_b32_e32 v66, s48, v150
	v_lshl_add_u32 v42, v66, 1, 0
	v_add_u32_e32 v0, v42, v151
	ds_read_u16 v43, v0
	ds_read_b128 v[34:37], v187 offset:32
	ds_read_b128 v[38:41], v187 offset:64
	s_waitcnt vmcnt(7) lgkmcnt(3)
	v_mfma_f32_32x32x16_bf16 v[18:33], v[2:5], v[114:117], 0
	s_waitcnt vmcnt(2)
	v_mfma_f32_32x32x16_bf16 v[2:17], v[2:5], v[134:137], 0
	s_waitcnt lgkmcnt(1)
	v_mfma_f32_32x32x16_bf16 v[18:33], v[34:37], v[118:121], v[18:33]
	v_mfma_f32_32x32x16_bf16 v[2:17], v[34:37], v[126:129], v[2:17]
	ds_read_b128 v[34:37], v187 offset:96
	s_waitcnt lgkmcnt(1)
	v_mfma_f32_32x32x16_bf16 v[18:33], v[38:41], v[122:125], v[18:33]
	s_waitcnt vmcnt(1) lgkmcnt(0)
	ds_read_u16 v82, v0 offset:1040
	ds_read_u16 v83, v0 offset:2080
	ds_read_u16 v84, v0 offset:3120
	v_add_u32_e32 v113, v42, v152
	ds_read_u16 v85, v113
	ds_read_u16 v86, v0 offset:9360
	ds_read_u16 v87, v0 offset:10400
	ds_read_u16 v88, v0 offset:11440
	ds_read_u16 v89, v113 offset:8320
	ds_read_u16 v90, v0 offset:17680
	ds_read_u16 v91, v0 offset:18720
	ds_read_u16 v92, v0 offset:19760
	ds_read_u16 v93, v0 offset:34320
	ds_read_u16 v94, v0 offset:35360
	ds_read_u16 v95, v0 offset:36400
	ds_read_u16 v96, v0 offset:41600
	ds_read_u16 v97, v0 offset:42640
	ds_read_u16 v98, v0 offset:43680
	ds_read_u16 v99, v0 offset:44720
	ds_read_u16 v100, v0 offset:49920
	ds_read_u16 v101, v0 offset:50960
	ds_read_u16 v102, v0 offset:52000
	ds_read_u16 v103, v0 offset:53040
	ds_read_u16 v104, v0 offset:58240
	ds_read_u16 v105, v0 offset:59280
	ds_read_u16 v106, v0 offset:60320
	v_mfma_f32_32x32x16_bf16 v[18:33], v[34:37], v[138:141], v[18:33]
	v_mfma_f32_32x32x16_bf16 v[2:17], v[38:41], v[130:133], v[2:17]
	s_nop 10
	v_add_f32_e32 v18, v192, v18
	v_mul_f32_e32 v18, 0xbfb8aa3b, v18
	v_exp_f32_e32 v18, v18
	v_add_f32_e32 v19, v192, v19
	v_mul_f32_e32 v19, 0xbfb8aa3b, v19
	v_exp_f32_e32 v19, v19
	v_add_f32_e32 v18, 1.0, v18
	s_waitcnt vmcnt(0)
	s_cmp_lg_u32 s80, 0
	s_cbranch_scc1 .Lscan_pf_no
	s_cmp_lg_u64 s[22:23], 0
	s_cbranch_scc0 .Lscan_pf_no
	s_add_i32 s98, s78, s24
	s_cmpk_ge_i32 s98, 0x200
	s_cbranch_scc1 .Lscan_pf_no
	s_lshr_b32 s99, s33, 6
	s_lshl_b32 s100, s98, 6
	s_add_i32 s100, s100, s99
	s_add_i32 s100, s100, -2
	s_mul_i32 s100, s100, 0xe00
	s_lshl_b32 s98, s98, 6
	s_and_b32 s98, s98, 0x3fc0
	s_add_i32 s98, s98, s99
	s_add_i32 s98, s98, -2
	s_lshl_b32 s99, s99, 10
	s_add_i32 s99, s99, s65
	s_add_u32 s100, s10, s100
	s_addc_u32 s101, s11, 0
	v_lshlrev_b32_e32 v112, 4, v188
	s_cmpk_lt_u32 s98, 0x4000
	s_cbranch_scc0 .Lscan_pf_s0
	s_mov_b32 m0, s99
	s_nop 0
	global_load_lds_dwordx4 v112, s[100:101]
.Lscan_pf_s0:
	s_add_i32 s98, s98, 8
	s_addk_i32 s99, 0x2000
	s_add_u32 s100, s100, 0x7000
	s_addc_u32 s101, s101, 0
	s_cmpk_lt_u32 s98, 0x4000
	s_cbranch_scc0 .Lscan_pf_s1
	s_mov_b32 m0, s99
	s_nop 0
	global_load_lds_dwordx4 v112, s[100:101]

; __device__ __forceinline__ float bf2f(bf16_t b) { return __uint_as_float(((unsigned)b) << 16); }
; __device__ __forceinline__ float fast_sigmoid(float x) { return __builtin_amdgcn_rcpf(1.0f + __builtin_amdgcn_exp2f(-1.4426950408889634f * x)); }
; template <int DIR>
; __device__ __forceinline__ void scan_dir(PP p, const bf16_t* xs, const ScanW& w, ScanW& wn, int ndir, int nct, bool do_next, int n, int ct, int l31, int hl, int id, int rowbase, bool latent, float (&hf)[2][16]) {
;     ...
; #pragma unroll
;         for (int i = 0; i < 16; ++i) {
;             const int token = 32 * rt + 8 * (i >> 2) + 4 * hl + (i & 3);
;             const float xv = bf2f(xs[token * XS + ch]);
;             const float rr = fast_sigmoid(ga[i] + ba), ii = fast_sigmoid(gi[i] + bi);
;             const float la2 = rr * sp8l2;
;             const float av = __builtin_amdgcn_exp2f(la2);
;             const float t2 = la2 * 1.3862943611f;
;             float em1p = t2 * (1.0f + t2 * (0.5f + t2 * (0.16666667f + t2 * (0.041666668f + t2 * 0.0083333333f)))), em1e = __builtin_fmaf(av, av, -1.0f);
;             asm volatile("" : "+v"(em1p), "+v"(em1e));
;             const float em1 = (t2 > -0.1f) ? em1p : em1e;
;             a[rt][i] = av; u[rt][i] = __builtin_amdgcn_sqrtf(-em1) * (ii * xv);
;         }
.Lscan_pf_s7:
	s_add_i32 s98, s98, 8
	s_addk_i32 s99, 0x2000
	s_add_u32 s100, s100, 0x7000
	s_addc_u32 s101, s101, 0
	s_cmpk_lt_u32 s98, 0x4000
	s_cbranch_scc0 .Lscan_pf_s8
	s_cmpk_lt_u32 s33, 0xc0
	s_cbranch_scc0 .Lscan_pf_s8
	s_mov_b32 m0, s99
	s_nop 0
	global_load_lds_dwordx4 v112, s[100:101]
.Lscan_pf_s8:
	s_mov_b32 s97, 1
.Lscan_pf_no:
	v_mfma_f32_32x32x16_bf16 v[2:17], v[34:37], v[142:145], v[2:17]
	v_rcp_f32_e32 v18, v18
	v_add_f32_e32 v19, 1.0, v19
	v_rcp_f32_e32 v19, v19
	v_lshlrev_b32_e32 v34, 16, v43
	v_mul_f32_e32 v18, v194, v18
	v_exp_f32_e32 v50, v18
	v_mul_f32_e32 v18, 0x3fb17218, v18
	s_nop 4
	v_add_f32_e32 v2, v191, v2
	v_mul_f32_e32 v2, 0xbfb8aa3b, v2
	v_exp_f32_e32 v2, v2
	v_fmamk_f32 v35, v18, 0x3c088888, v186
	v_fmaak_f32 v35, v18, v35, 0x3e2aaaab
	v_fma_f32 v35, v18, v35, 0.5
	v_add_f32_e32 v2, 1.0, v2
	v_add_f32_e32 v3, v191, v3
	v_rcp_f32_e32 v2, v2
	v_fma_f32 v35, v18, v35, 1.0
	v_mul_f32_e32 v3, 0xbfb8aa3b, v3
	v_mul_f32_e32 v35, v18, v35
	v_fma_f32 v36, v50, v50, -1.0
	v_exp_f32_e32 v3, v3
	v_mul_f32_e32 v19, v194, v19
	v_cmp_lt_f32_e32 vcc, s76, v18
	v_exp_f32_e32 v52, v19
	v_mul_f32_e32 v19, 0x3fb17218, v19
	v_cndmask_b32_e32 v18, v36, v35, vcc
	v_fmamk_f32 v35, v19, 0x3c088888, v186
	v_mul_f32_e32 v2, v2, v34
	v_fmaak_f32 v35, v19, v35, 0x3e2aaaab
	v_sqrt_f32_e64 v18, -v18
	v_add_f32_e32 v3, 1.0, v3
	v_fma_f32 v35, v19, v35, 0.5
	v_add_f32_e32 v4, v191, v4
	v_rcp_f32_e32 v3, v3
	v_fma_f32 v35, v19, v35, 1.0
	v_mul_f32_e32 v4, 0xbfb8aa3b, v4
	v_mul_f32_e32 v35, v19, v35
	v_fma_f32 v36, v52, v52, -1.0
	v_cmp_lt_f32_e32 vcc, s76, v19
	v_exp_f32_e32 v4, v4
	v_mul_f32_e32 v2, v2, v18
	v_cndmask_b32_e32 v19, v36, v35, vcc
	v_sqrt_f32_e64 v19, -v19
	s_waitcnt lgkmcnt(0)
	v_lshlrev_b32_e32 v18, 16, v82
	v_mul_f32_e32 v3, v3, v18
	v_add_f32_e32 v4, 1.0, v4
	v_rcp_f32_e32 v4, v4
	v_mul_f32_e32 v3, v3, v19
	v_add_f32_e32 v19, v192, v20
	v_mul_f32_e32 v19, 0xbfb8aa3b, v19
	v_exp_f32_e32 v19, v19
	s_waitcnt lgkmcnt(0)
	v_lshlrev_b32_e32 v18, 16, v83
	v_mul_f32_e32 v4, v4, v18
	v_add_f32_e32 v18, v192, v21
	v_mul_f32_e32 v18, 0xbfb8aa3b, v18
	v_exp_f32_e32 v18, v18
	v_add_f32_e32 v19, 1.0, v19
	v_rcp_f32_e32 v19, v19
	v_add_f32_e32 v5, v191, v5
	v_add_f32_e32 v18, 1.0, v18
	v_rcp_f32_e32 v18, v18
	v_mul_f32_e32 v19, v194, v19
	v_exp_f32_e32 v51, v19
	v_mul_f32_e32 v19, 0x3fb17218, v19
	v_fmamk_f32 v20, v19, 0x3c088888, v186
	v_fmaak_f32 v20, v19, v20, 0x3e2aaaab
	v_mul_f32_e32 v18, v194, v18
	v_fma_f32 v20, v19, v20, 0.5
	v_mul_f32_e32 v5, 0xbfb8aa3b, v5
	v_exp_f32_e32 v54, v18
	v_mul_f32_e32 v18, 0x3fb17218, v18
	v_fma_f32 v20, v19, v20, 1.0
	v_exp_f32_e32 v5, v5
	v_fmamk_f32 v21, v18, 0x3c088888, v186
	v_mul_f32_e32 v20, v19, v20
	v_fma_f32 v34, v51, v51, -1.0
	v_fmaak_f32 v21, v18, v21, 0x3e2aaaab
	v_cmp_lt_f32_e32 vcc, s76, v19
	v_fma_f32 v21, v18, v21, 0.5
	v_fma_f32 v21, v18, v21, 1.0
	v_cndmask_b32_e32 v19, v34, v20, vcc
	v_sqrt_f32_e64 v19, -v19
	v_add_f32_e32 v5, 1.0, v5
	v_mul_f32_e32 v21, v18, v21
	v_fma_f32 v34, v54, v54, -1.0
	v_cmp_lt_f32_e32 vcc, s76, v18
	v_rcp_f32_e32 v5, v5
	v_add_f32_e32 v6, v191, v6
	v_cndmask_b32_e32 v18, v34, v21, vcc
	v_sqrt_f32_e64 v18, -v18
	v_mul_f32_e32 v6, 0xbfb8aa3b, v6
	v_mul_f32_e32 v4, v4, v19
	s_waitcnt lgkmcnt(0)
	v_lshlrev_b32_e32 v19, 16, v84
	v_exp_f32_e32 v6, v6
	v_mul_f32_e32 v5, v5, v19
	v_mul_f32_e32 v5, v18, v5
	v_add_u32_e32 v18, v42, v152
	v_add_f32_e32 v20, v192, v22
	v_mul_f32_e32 v20, 0xbfb8aa3b, v20
	v_add_f32_e32 v6, 1.0, v6
	v_exp_f32_e32 v20, v20
	v_rcp_f32_e32 v6, v6
	s_waitcnt lgkmcnt(0)
	v_lshlrev_b32_e32 v19, 16, v85
	v_add_f32_e32 v7, v191, v7
	v_add_f32_e32 v20, 1.0, v20
	v_mul_f32_e32 v6, v6, v19
	v_add_f32_e32 v19, v192, v23
	v_rcp_f32_e32 v20, v20
	v_mul_f32_e32 v19, 0xbfb8aa3b, v19
	v_exp_f32_e32 v19, v19
	v_mul_f32_e32 v7, 0xbfb8aa3b, v7
	v_mul_f32_e32 v20, v194, v20
	v_exp_f32_e32 v53, v20
	v_mul_f32_e32 v20, 0x3fb17218, v20
	v_add_f32_e32 v19, 1.0, v19
	v_fmamk_f32 v21, v20, 0x3c088888, v186
	v_rcp_f32_e32 v19, v19
	v_fmaak_f32 v21, v20, v21, 0x3e2aaaab
	v_fma_f32 v21, v20, v21, 0.5
	v_fma_f32 v21, v20, v21, 1.0
	v_mul_f32_e32 v21, v20, v21
	v_fma_f32 v22, v53, v53, -1.0
	v_mul_f32_e32 v19, v194, v19
	v_cmp_lt_f32_e32 vcc, s76, v20
	v_exp_f32_e32 v55, v19
	v_mul_f32_e32 v19, 0x3fb17218, v19
	v_cndmask_b32_e32 v20, v22, v21, vcc
	v_exp_f32_e32 v7, v7
	v_fmamk_f32 v22, v19, 0x3c088888, v186
	v_fmaak_f32 v22, v19, v22, 0x3e2aaaab
	v_fma_f32 v22, v19, v22, 0.5
	v_fma_f32 v22, v19, v22, 1.0
	v_sqrt_f32_e64 v20, -v20
	v_add_f32_e32 v7, 1.0, v7
	v_mul_f32_e32 v22, v19, v22
	v_fma_f32 v23, v55, v55, -1.0
	v_cmp_lt_f32_e32 vcc, s76, v19
	v_rcp_f32_e32 v7, v7
	v_add_f32_e32 v8, v191, v8
	v_cndmask_b32_e32 v19, v23, v22, vcc
	v_sqrt_f32_e64 v19, -v19
	v_mul_f32_e32 v8, 0xbfb8aa3b, v8
	v_exp_f32_e32 v8, v8
	v_mul_f32_e32 v6, v20, v6
	s_waitcnt lgkmcnt(0)
	v_lshlrev_b32_e32 v20, 16, v86
	v_mul_f32_e32 v7, v7, v20
	v_mul_f32_e32 v7, v19, v7
	v_add_f32_e32 v20, v192, v24
	v_mul_f32_e32 v20, 0xbfb8aa3b, v20
	v_add_f32_e32 v8, 1.0, v8
	v_exp_f32_e32 v20, v20
	v_rcp_f32_e32 v8, v8
	s_waitcnt lgkmcnt(0)
; __device__ __forceinline__ float bf2f(bf16_t b) { return __uint_as_float(((unsigned)b) << 16); }
; __device__ __forceinline__ float fast_sigmoid(float x) { return __builtin_amdgcn_rcpf(1.0f + __builtin_amdgcn_exp2f(-1.4426950408889634f * x)); }
; template <int DIR>
; __device__ __forceinline__ void scan_dir(PP p, const bf16_t* xs, const ScanW& w, ScanW& wn, int ndir, int nct, bool do_next, int n, int ct, int l31, int hl, int id, int rowbase, bool latent, float (&hf)[2][16]) {
;     ...
; #pragma unroll
;         for (int i = 0; i < 16; ++i) {
;             const int token = 32 * rt + 8 * (i >> 2) + 4 * hl + (i & 3);
;             const float xv = bf2f(xs[token * XS + ch]);
;             const float rr = fast_sigmoid(ga[i] + ba), ii = fast_sigmoid(gi[i] + bi);
;             const float la2 = rr * sp8l2;
;             const float av = __builtin_amdgcn_exp2f(la2);
;             const float t2 = la2 * 1.3862943611f;
;             float em1p = t2 * (1.0f + t2 * (0.5f + t2 * (0.16666667f + t2 * (0.041666668f + t2 * 0.0083333333f)))), em1e = __builtin_fmaf(av, av, -1.0f);
;             asm volatile("" : "+v"(em1p), "+v"(em1e));
;             const float em1 = (t2 > -0.1f) ? em1p : em1e;
;             a[rt][i] = av; u[rt][i] = __builtin_amdgcn_sqrtf(-em1) * (ii * xv);
;         }
	v_lshlrev_b32_e32 v19, 16, v87
	v_add_f32_e32 v9, v191, v9
	v_add_f32_e32 v20, 1.0, v20
	v_mul_f32_e32 v8, v8, v19
	v_add_f32_e32 v19, v192, v25
	v_rcp_f32_e32 v20, v20
	v_mul_f32_e32 v19, 0xbfb8aa3b, v19
	v_exp_f32_e32 v19, v19
	v_mul_f32_e32 v9, 0xbfb8aa3b, v9
	v_mul_f32_e32 v20, v194, v20
	v_exp_f32_e32 v67, v20
	v_mul_f32_e32 v20, 0x3fb17218, v20
	v_add_f32_e32 v19, 1.0, v19
	v_fmamk_f32 v21, v20, 0x3c088888, v186
	v_rcp_f32_e32 v19, v19
	v_fmaak_f32 v21, v20, v21, 0x3e2aaaab
	v_fma_f32 v21, v20, v21, 0.5
	v_fma_f32 v21, v20, v21, 1.0
	v_mul_f32_e32 v21, v20, v21
	v_fma_f32 v22, v67, v67, -1.0
	v_mul_f32_e32 v19, v194, v19
	v_cmp_lt_f32_e32 vcc, s76, v20
	v_exp_f32_e32 v69, v19
	v_mul_f32_e32 v19, 0x3fb17218, v19
	v_cndmask_b32_e32 v20, v22, v21, vcc
	v_exp_f32_e32 v9, v9
	v_fmamk_f32 v22, v19, 0x3c088888, v186
	v_fmaak_f32 v22, v19, v22, 0x3e2aaaab
	v_fma_f32 v22, v19, v22, 0.5
	v_fma_f32 v22, v19, v22, 1.0
	v_sqrt_f32_e64 v20, -v20
	v_add_f32_e32 v9, 1.0, v9
	v_mul_f32_e32 v22, v19, v22
	v_fma_f32 v23, v69, v69, -1.0
	v_cmp_lt_f32_e32 vcc, s76, v19
	v_rcp_f32_e32 v9, v9
	v_add_f32_e32 v10, v191, v10
	v_cndmask_b32_e32 v19, v23, v22, vcc
	v_sqrt_f32_e64 v19, -v19
	v_mul_f32_e32 v10, 0xbfb8aa3b, v10
	v_exp_f32_e32 v10, v10
	v_mul_f32_e32 v8, v20, v8
	s_waitcnt lgkmcnt(0)
	v_lshlrev_b32_e32 v20, 16, v88
	v_mul_f32_e32 v9, v9, v20
	v_mul_f32_e32 v76, v19, v9
	v_add_f32_e32 v19, v192, v26
	v_mul_f32_e32 v19, 0xbfb8aa3b, v19
	v_add_f32_e32 v10, 1.0, v10
	v_exp_f32_e32 v19, v19
	v_rcp_f32_e32 v10, v10
	s_waitcnt lgkmcnt(0)
	v_lshlrev_b32_e32 v9, 16, v89
	v_add_f32_e32 v11, v191, v11
	v_add_f32_e32 v19, 1.0, v19
	v_mul_f32_e32 v9, v10, v9
	v_add_f32_e32 v10, v192, v27
	v_rcp_f32_e32 v19, v19
	v_mul_f32_e32 v10, 0xbfb8aa3b, v10
	v_exp_f32_e32 v10, v10
	v_mul_f32_e32 v11, 0xbfb8aa3b, v11
	v_mul_f32_e32 v19, v194, v19
	v_exp_f32_e32 v68, v19
	v_mul_f32_e32 v19, 0x3fb17218, v19
	v_add_f32_e32 v10, 1.0, v10
	v_fmamk_f32 v20, v19, 0x3c088888, v186
	v_rcp_f32_e32 v10, v10
	v_fmaak_f32 v20, v19, v20, 0x3e2aaaab
	v_fma_f32 v20, v19, v20, 0.5
	v_fma_f32 v20, v19, v20, 1.0
	v_mul_f32_e32 v20, v19, v20
	v_fma_f32 v21, v68, v68, -1.0
	v_mul_f32_e32 v10, v194, v10
	v_cmp_lt_f32_e32 vcc, s76, v19
	v_exp_f32_e32 v71, v10
	v_mul_f32_e32 v10, 0x3fb17218, v10
	v_cndmask_b32_e32 v19, v21, v20, vcc
	v_exp_f32_e32 v11, v11
	v_fmamk_f32 v21, v10, 0x3c088888, v186
	v_fmaak_f32 v21, v10, v21, 0x3e2aaaab
	v_fma_f32 v21, v10, v21, 0.5
	v_fma_f32 v21, v10, v21, 1.0
	v_sqrt_f32_e64 v19, -v19
	v_add_f32_e32 v11, 1.0, v11
	v_mul_f32_e32 v21, v10, v21
	v_fma_f32 v22, v71, v71, -1.0
	v_cmp_lt_f32_e32 vcc, s76, v10
	v_rcp_f32_e32 v11, v11
	v_mul_f32_e32 v74, v19, v9
	v_cndmask_b32_e32 v10, v22, v21, vcc
	v_sqrt_f32_e64 v10, -v10
	s_waitcnt lgkmcnt(0)
	v_lshlrev_b32_e32 v9, 16, v90
	v_mul_f32_e32 v9, v11, v9
	v_add_f32_e32 v11, v191, v12
	v_mul_f32_e32 v73, v10, v9
	v_add_f32_e32 v10, v192, v28
	v_mul_f32_e32 v10, 0xbfb8aa3b, v10
	v_exp_f32_e32 v10, v10
	v_mul_f32_e32 v11, 0xbfb8aa3b, v11
	v_exp_f32_e32 v11, v11
	v_add_f32_e32 v10, 1.0, v10
	v_rcp_f32_e32 v10, v10
	s_waitcnt lgkmcnt(0)
	v_lshlrev_b32_e32 v9, 16, v91
	v_add_f32_e32 v11, 1.0, v11
	v_rcp_f32_e32 v11, v11
	v_mul_f32_e32 v10, v194, v10
	v_exp_f32_e32 v70, v10
	v_mul_f32_e32 v10, 0x3fb17218, v10
	v_fmamk_f32 v12, v10, 0x3c088888, v186
	v_fmaak_f32 v12, v10, v12, 0x3e2aaaab
	v_fma_f32 v12, v10, v12, 0.5
	v_fma_f32 v12, v10, v12, 1.0
	v_mul_f32_e32 v12, v10, v12
	v_fma_f32 v19, v70, v70, -1.0
	v_cmp_lt_f32_e32 vcc, s76, v10
	v_mul_f32_e32 v9, v11, v9
	v_add_f32_e32 v11, v191, v13
	v_cndmask_b32_e32 v10, v19, v12, vcc
	v_add_f32_e32 v12, v192, v29
	v_mul_f32_e32 v12, 0xbfb8aa3b, v12
	v_exp_f32_e32 v12, v12
	v_sqrt_f32_e64 v19, -v10
	v_mul_f32_e32 v11, 0xbfb8aa3b, v11
	v_exp_f32_e32 v21, v11
	v_add_f32_e32 v10, 1.0, v12
	v_rcp_f32_e32 v10, v10
	v_add_f32_e32 v11, v192, v30
	v_mul_f32_e32 v11, 0xbfb8aa3b, v11
	v_exp_f32_e32 v11, v11
	v_mul_f32_e32 v10, v194, v10
	v_mul_f32_e32 v22, 0x3fb17218, v10
	v_exp_f32_e32 v75, v10
	v_fmamk_f32 v10, v22, 0x3c088888, v186
	v_fmaak_f32 v10, v22, v10, 0x3e2aaaab
	v_fma_f32 v10, v22, v10, 0.5
	v_fma_f32 v10, v22, v10, 1.0
	v_mul_f32_e32 v23, v22, v10
	v_add_f32_e32 v10, 1.0, v11
	v_rcp_f32_e32 v10, v10
	v_add_f32_e32 v11, v192, v31
	v_mul_f32_e32 v11, 0xbfb8aa3b, v11
	v_exp_f32_e32 v11, v11
	v_mul_f32_e32 v10, v194, v10
	v_mul_f32_e32 v60, 0x3fb17218, v10
	v_exp_f32_e32 v72, v10
	v_fmamk_f32 v10, v60, 0x3c088888, v186
	v_fmaak_f32 v10, v60, v10, 0x3e2aaaab
	v_fma_f32 v10, v60, v10, 0.5
	v_fma_f32 v10, v60, v10, 1.0
	v_mul_f32_e32 v61, v60, v10
	v_add_f32_e32 v10, 1.0, v11
	v_rcp_f32_e32 v10, v10
	v_add_f32_e32 v11, v192, v32
	v_mul_f32_e32 v11, 0xbfb8aa3b, v11
	v_exp_f32_e32 v11, v11
	v_mul_f32_e32 v10, v194, v10
	v_mul_f32_e32 v64, 0x3fb17218, v10
	v_exp_f32_e32 v78, v10
	v_fmamk_f32 v10, v64, 0x3c088888, v186
	v_fmaak_f32 v10, v64, v10, 0x3e2aaaab
	v_fma_f32 v10, v64, v10, 0.5
	v_fma_f32 v10, v64, v10, 1.0
	v_mul_f32_e32 v65, v64, v10
	v_add_f32_e32 v10, 1.0, v11
	v_rcp_f32_e32 v10, v10
	v_add_f32_e32 v11, v192, v33
	v_mul_f32_e32 v11, 0xbfb8aa3b, v11
	v_exp_f32_e32 v11, v11
	v_mul_f32_e32 v10, v194, v10
	v_mul_f32_e32 v146, 0x3fb17218, v10
	v_exp_f32_e32 v77, v10
	v_fmamk_f32 v10, v146, 0x3c088888, v186
	v_fmaak_f32 v10, v146, v10, 0x3e2aaaab
	v_fma_f32 v10, v146, v10, 0.5
	v_fma_f32 v10, v146, v10, 1.0
	v_mul_f32_e32 v147, v146, v10
	v_add_f32_e32 v10, 1.0, v11
	v_rcp_f32_e32 v10, v10
	v_fma_f32 v24, v75, v75, -1.0
	v_mul_f32_e32 v209, v19, v9
	v_mul_f32_e32 v10, v194, v10
	v_mul_f32_e32 v156, 0x3fb17218, v10
	v_add_f32_e32 v19, 1.0, v21
	v_cmp_lt_f32_e32 vcc, s76, v22
	v_exp_f32_e32 v79, v10
	v_fmamk_f32 v10, v156, 0x3c088888, v186
	v_rcp_f32_e32 v35, v19
	v_cndmask_b32_e32 v19, v24, v23, vcc
	v_fmaak_f32 v10, v156, v10, 0x3e2aaaab
	v_sqrt_f32_e64 v36, -v19
	v_fma_f32 v10, v156, v10, 0.5
	v_fma_f32 v10, v156, v10, 1.0
	s_waitcnt lgkmcnt(0)
; __device__ __forceinline__ float bf2f(bf16_t b) { return __uint_as_float(((unsigned)b) << 16); }
; __device__ __forceinline__ float fast_sigmoid(float x) { return __builtin_amdgcn_rcpf(1.0f + __builtin_amdgcn_exp2f(-1.4426950408889634f * x)); }
; template <int DIR>
; __device__ __forceinline__ void scan_dir(PP p, const bf16_t* xs, const ScanW& w, ScanW& wn, int ndir, int nct, bool do_next, int n, int ct, int l31, int hl, int id, int rowbase, bool latent, float (&hf)[2][16]) {
;     ...
;         bf16x8 af[4];
; #pragma unroll
;         for (int st = 0; st < 4; ++st) af[st] = *(const bf16x8*)(xs + (32 * rt + l31) * XS + 64 * n + 16 * st + 8 * hl);
;         f32x16 ga, gi;
; #pragma unroll
;         for (int i = 0; i < 16; ++i) { ga[i] = 0.f; gi[i] = 0.f; }
; #pragma unroll
;         for (int st = 0; st < 4; ++st) { ga = __builtin_amdgcn_mfma_f32_32x32x16_bf16(af[st], wfa[st], ga, 0, 0, 0); gi = __builtin_amdgcn_mfma_f32_32x32x16_bf16(af[st], wfi[st], gi, 0, 0, 0); }
; #pragma unroll
;         for (int i = 0; i < 16; ++i) {
;             const int token = 32 * rt + 8 * (i >> 2) + 4 * hl + (i & 3);
;             const float xv = bf2f(xs[token * XS + ch]);
;             const float rr = fast_sigmoid(ga[i] + ba), ii = fast_sigmoid(gi[i] + bi);
;             const float la2 = rr * sp8l2;
;             const float av = __builtin_amdgcn_exp2f(la2);
;             const float t2 = la2 * 1.3862943611f;
;             float em1p = t2 * (1.0f + t2 * (0.5f + t2 * (0.16666667f + t2 * (0.041666668f + t2 * 0.0083333333f)))), em1e = __builtin_fmaf(av, av, -1.0f);
;             asm volatile("" : "+v"(em1p), "+v"(em1e));
;             const float em1 = (t2 > -0.1f) ? em1p : em1e;
;             a[rt][i] = av; u[rt][i] = __builtin_amdgcn_sqrtf(-em1) * (ii * xv);
;         }
	v_lshlrev_b32_e32 v9, 16, v92
	v_fma_f32 v62, v72, v72, -1.0
	v_fma_f32 v80, v78, v78, -1.0
	v_fma_f32 v154, v77, v77, -1.0
	v_mul_f32_e32 v158, v156, v10
	v_fma_f32 v159, v79, v79, -1.0
	v_mul_f32_e32 v9, v35, v9
	ds_read_u16 v34, v18 offset:16640
	ds_read_u16 v63, v0 offset:26000
	ds_read_u16 v81, v0 offset:27040
	ds_read_u16 v155, v0 offset:28080
	ds_read_b128 v[10:13], v187 offset:33280
	ds_read_u16 v195, v18 offset:24960
	v_mul_f32_e32 v217, v36, v9
	v_add_f32_e32 v9, v191, v14
	v_mul_f32_e32 v9, 0xbfb8aa3b, v9
	v_exp_f32_e32 v9, v9
	v_add_f32_e32 v15, v191, v15
	v_mul_f32_e32 v15, 0xbfb8aa3b, v15
	v_exp_f32_e32 v15, v15
	v_add_f32_e32 v9, 1.0, v9
	v_rcp_f32_e32 v9, v9
	ds_read_b128 v[56:59], v187 offset:33312
	s_waitcnt lgkmcnt(6)
	v_lshlrev_b32_e32 v14, 16, v34
	s_waitcnt lgkmcnt(2)
	v_mfma_f32_32x32x16_bf16 v[34:49], v[10:13], v[134:137], 0
	v_cmp_lt_f32_e32 vcc, s76, v60
	v_mul_f32_e32 v9, v9, v14
	v_add_f32_e32 v14, 1.0, v15
	v_rcp_f32_e32 v14, v14
	v_mfma_f32_32x32x16_bf16 v[18:33], v[10:13], v[114:117], 0
	v_cndmask_b32_e32 v10, v62, v61, vcc
	v_sqrt_f32_e64 v60, -v10
	ds_read_b128 v[10:13], v187 offset:33344
	v_cmp_lt_f32_e32 vcc, s76, v64
	v_mul_f32_e32 v197, v60, v9
	v_lshlrev_b32_e32 v9, 16, v63
	v_mul_f32_e32 v9, v14, v9
	v_add_f32_e32 v14, v191, v16
	s_waitcnt lgkmcnt(1)
	v_mfma_f32_32x32x16_bf16 v[34:49], v[56:59], v[126:129], v[34:49]
	v_mul_f32_e32 v14, 0xbfb8aa3b, v14
	v_exp_f32_e32 v14, v14
	v_cndmask_b32_e32 v15, v80, v65, vcc
	v_sqrt_f32_e64 v15, -v15
	v_cmp_lt_f32_e32 vcc, s76, v146
	v_add_f32_e32 v14, 1.0, v14
	v_mul_f32_e32 v199, v15, v9
	v_mfma_f32_32x32x16_bf16 v[18:33], v[56:59], v[118:121], v[18:33]
	v_rcp_f32_e32 v56, v14
	v_add_f32_e32 v14, v191, v17
	v_mul_f32_e32 v57, 0xbfb8aa3b, v14
	ds_read_b128 v[14:17], v187 offset:33376
	v_lshlrev_b32_e32 v9, 16, v81
	v_mul_f32_e32 v9, v56, v9
	s_waitcnt lgkmcnt(1)
	v_mfma_f32_32x32x16_bf16 v[34:49], v[10:13], v[130:133], v[34:49]
	v_mfma_f32_32x32x16_bf16 v[18:33], v[10:13], v[122:125], v[18:33]
	v_exp_f32_e32 v10, v57
	v_cndmask_b32_e32 v11, v154, v147, vcc
	v_sqrt_f32_e64 v11, -v11
	v_cmp_lt_f32_e32 vcc, s76, v156
	v_add_f32_e32 v10, 1.0, v10
	v_rcp_f32_e32 v10, v10
	v_cndmask_b32_e32 v12, v159, v158, vcc
	s_waitcnt lgkmcnt(0)
	v_mfma_f32_32x32x16_bf16 v[34:49], v[14:17], v[142:145], v[34:49]
	v_sqrt_f32_e64 v12, -v12
	v_mul_f32_e32 v204, v11, v9
	v_lshlrev_b32_e32 v9, 16, v155
	v_mul_f32_e32 v9, v10, v9
	v_mul_f32_e32 v202, v12, v9
	v_lshlrev_b32_e32 v11, 16, v195
	s_nop 5
	v_add_f32_e32 v10, v191, v34
	v_mfma_f32_32x32x16_bf16 v[18:33], v[14:17], v[138:141], v[18:33]
	v_mul_f32_e32 v10, 0xbfb8aa3b, v10
	v_exp_f32_e32 v10, v10
	s_nop 0
	v_add_f32_e32 v10, 1.0, v10
	v_rcp_f32_e32 v10, v10
	s_nop 6
	v_add_f32_e32 v9, v192, v18
	v_mul_f32_e32 v9, 0xbfb8aa3b, v9
	v_exp_f32_e32 v9, v9
	v_mul_f32_e32 v10, v10, v11
	v_add_f32_e32 v11, v192, v19
	v_mul_f32_e32 v11, 0xbfb8aa3b, v11
	v_add_f32_e32 v9, 1.0, v9
	v_rcp_f32_e32 v9, v9
	v_exp_f32_e32 v11, v11
	v_mul_f32_e32 v9, v194, v9
	v_exp_f32_e32 v80, v9
	v_mul_f32_e32 v9, 0x3fb17218, v9
	v_fmamk_f32 v12, v9, 0x3c088888, v186
	v_fmaak_f32 v12, v9, v12, 0x3e2aaaab
	v_add_f32_e32 v11, 1.0, v11
	v_fma_f32 v12, v9, v12, 0.5
	v_rcp_f32_e32 v11, v11
	v_fma_f32 v12, v9, v12, 1.0
	v_mul_f32_e32 v12, v9, v12
	v_fma_f32 v13, v80, v80, -1.0
	v_cmp_lt_f32_e32 vcc, s76, v9
	v_mul_f32_e32 v11, v194, v11
	v_exp_f32_e32 v146, v11
	v_cndmask_b32_e32 v9, v13, v12, vcc
	v_add_f32_e32 v12, v191, v35
	v_mul_f32_e32 v12, 0xbfb8aa3b, v12
	v_mul_f32_e32 v11, 0x3fb17218, v11
	v_exp_f32_e32 v12, v12
	v_fmamk_f32 v14, v11, 0x3c088888, v186
	v_fmaak_f32 v14, v11, v14, 0x3e2aaaab
	v_fma_f32 v14, v11, v14, 0.5
	v_fma_f32 v14, v11, v14, 1.0
	v_sqrt_f32_e64 v9, -v9
	v_add_f32_e32 v12, 1.0, v12
	v_mul_f32_e32 v14, v11, v14
	v_fma_f32 v15, v146, v146, -1.0
	v_cmp_lt_f32_e32 vcc, s76, v11
	v_rcp_f32_e32 v12, v12
	v_mul_f32_e32 v196, v10, v9
	v_cndmask_b32_e32 v11, v15, v14, vcc
	v_sqrt_f32_e64 v11, -v11
	s_waitcnt lgkmcnt(0)
	v_lshlrev_b32_e32 v9, 16, v93
	v_mul_f32_e32 v9, v12, v9
	v_add_f32_e32 v10, v192, v20
	v_mul_f32_e32 v195, v9, v11
	v_add_f32_e32 v11, v191, v36
	v_mul_f32_e32 v11, 0xbfb8aa3b, v11
	v_exp_f32_e32 v11, v11
	v_mul_f32_e32 v10, 0xbfb8aa3b, v10
	v_exp_f32_e32 v10, v10
	v_add_f32_e32 v11, 1.0, v11
	v_rcp_f32_e32 v11, v11
	v_add_f32_e32 v10, 1.0, v10
	v_rcp_f32_e32 v10, v10
	s_waitcnt lgkmcnt(0)
	v_lshlrev_b32_e32 v9, 16, v94
	v_mul_f32_e32 v9, v11, v9
	v_add_f32_e32 v11, v192, v21
	v_mul_f32_e32 v11, 0xbfb8aa3b, v11
	v_exp_f32_e32 v11, v11
	v_mul_f32_e32 v10, v194, v10
	v_exp_f32_e32 v81, v10
	v_mul_f32_e32 v10, 0x3fb17218, v10
	v_fmamk_f32 v12, v10, 0x3c088888, v186
	v_fmaak_f32 v12, v10, v12, 0x3e2aaaab
	v_add_f32_e32 v11, 1.0, v11
	v_fma_f32 v12, v10, v12, 0.5
	v_rcp_f32_e32 v11, v11
	v_fma_f32 v12, v10, v12, 1.0
	v_mul_f32_e32 v12, v10, v12
	v_fma_f32 v13, v81, v81, -1.0
	v_cmp_lt_f32_e32 vcc, s76, v10
	v_mul_f32_e32 v11, v194, v11
	v_exp_f32_e32 v198, v11
	v_cndmask_b32_e32 v10, v13, v12, vcc
	v_add_f32_e32 v12, v191, v37
	v_mul_f32_e32 v12, 0xbfb8aa3b, v12
	v_mul_f32_e32 v11, 0x3fb17218, v11
	v_exp_f32_e32 v12, v12
	v_fmamk_f32 v14, v11, 0x3c088888, v186
	v_fmaak_f32 v14, v11, v14, 0x3e2aaaab
	v_fma_f32 v14, v11, v14, 0.5
	v_fma_f32 v14, v11, v14, 1.0
	v_sqrt_f32_e64 v10, -v10
	v_add_f32_e32 v12, 1.0, v12
	v_mul_f32_e32 v14, v11, v14
	v_fma_f32 v15, v198, v198, -1.0
	v_cmp_lt_f32_e32 vcc, s76, v11
	v_rcp_f32_e32 v12, v12
	v_mul_f32_e32 v214, v9, v10
	v_cndmask_b32_e32 v11, v15, v14, vcc
	v_sqrt_f32_e64 v11, -v11
	s_waitcnt lgkmcnt(0)
; __device__ __forceinline__ float bf2f(bf16_t b) { return __uint_as_float(((unsigned)b) << 16); }
; __device__ __forceinline__ float fast_sigmoid(float x) { return __builtin_amdgcn_rcpf(1.0f + __builtin_amdgcn_exp2f(-1.4426950408889634f * x)); }
; template <int DIR>
; __device__ __forceinline__ void scan_dir(PP p, const bf16_t* xs, const ScanW& w, ScanW& wn, int ndir, int nct, bool do_next, int n, int ct, int l31, int hl, int id, int rowbase, bool latent, float (&hf)[2][16]) {
;     ...
; #pragma unroll
;         for (int i = 0; i < 16; ++i) {
;             const int token = 32 * rt + 8 * (i >> 2) + 4 * hl + (i & 3);
;             const float xv = bf2f(xs[token * XS + ch]);
;             const float rr = fast_sigmoid(ga[i] + ba), ii = fast_sigmoid(gi[i] + bi);
;             const float la2 = rr * sp8l2;
;             const float av = __builtin_amdgcn_exp2f(la2);
;             const float t2 = la2 * 1.3862943611f;
;             float em1p = t2 * (1.0f + t2 * (0.5f + t2 * (0.16666667f + t2 * (0.041666668f + t2 * 0.0083333333f)))), em1e = __builtin_fmaf(av, av, -1.0f);
;             asm volatile("" : "+v"(em1p), "+v"(em1e));
;             const float em1 = (t2 > -0.1f) ? em1p : em1e;
;             a[rt][i] = av; u[rt][i] = __builtin_amdgcn_sqrtf(-em1) * (ii * xv);
;         }
	v_lshlrev_b32_e32 v9, 16, v95
	v_mul_f32_e32 v9, v12, v9
	v_add_f32_e32 v10, v192, v22
	v_mul_f32_e32 v211, v11, v9
	v_add_f32_e32 v11, v191, v38
	v_mul_f32_e32 v11, 0xbfb8aa3b, v11
	v_exp_f32_e32 v11, v11
	v_mul_f32_e32 v10, 0xbfb8aa3b, v10
	v_exp_f32_e32 v10, v10
	v_add_f32_e32 v11, 1.0, v11
	v_rcp_f32_e32 v11, v11
	v_add_f32_e32 v10, 1.0, v10
	v_rcp_f32_e32 v10, v10
	s_waitcnt lgkmcnt(0)
	v_lshlrev_b32_e32 v9, 16, v96
	v_mul_f32_e32 v9, v11, v9
	v_add_f32_e32 v11, v192, v23
	v_mul_f32_e32 v11, 0xbfb8aa3b, v11
	v_exp_f32_e32 v11, v11
	v_mul_f32_e32 v10, v194, v10
	v_exp_f32_e32 v147, v10
	v_mul_f32_e32 v10, 0x3fb17218, v10
	v_fmamk_f32 v12, v10, 0x3c088888, v186
	v_fmaak_f32 v12, v10, v12, 0x3e2aaaab
	v_add_f32_e32 v11, 1.0, v11
	v_fma_f32 v12, v10, v12, 0.5
	v_rcp_f32_e32 v11, v11
	v_fma_f32 v12, v10, v12, 1.0
	v_mul_f32_e32 v12, v10, v12
	v_fma_f32 v13, v147, v147, -1.0
	v_cmp_lt_f32_e32 vcc, s76, v10
	v_mul_f32_e32 v11, v194, v11
	v_exp_f32_e32 v201, v11
	v_cndmask_b32_e32 v10, v13, v12, vcc
	v_add_f32_e32 v12, v191, v39
	v_mul_f32_e32 v12, 0xbfb8aa3b, v12
	v_mul_f32_e32 v11, 0x3fb17218, v11
	v_exp_f32_e32 v12, v12
	v_fmamk_f32 v14, v11, 0x3c088888, v186
	v_fmaak_f32 v14, v11, v14, 0x3e2aaaab
	v_fma_f32 v14, v11, v14, 0.5
	v_fma_f32 v14, v11, v14, 1.0
	v_sqrt_f32_e64 v10, -v10
	v_add_f32_e32 v12, 1.0, v12
	v_mul_f32_e32 v14, v11, v14
	v_fma_f32 v15, v201, v201, -1.0
	v_cmp_lt_f32_e32 vcc, s76, v11
	v_rcp_f32_e32 v12, v12
	v_mul_f32_e32 v206, v10, v9
	v_cndmask_b32_e32 v11, v15, v14, vcc
	v_sqrt_f32_e64 v11, -v11
	s_waitcnt lgkmcnt(0)
	v_lshlrev_b32_e32 v9, 16, v97
	v_mul_f32_e32 v9, v12, v9
	v_add_f32_e32 v10, v192, v24
	v_mul_f32_e32 v205, v11, v9
	v_add_f32_e32 v11, v191, v40
	v_mul_f32_e32 v11, 0xbfb8aa3b, v11
	v_exp_f32_e32 v11, v11
	v_mul_f32_e32 v10, 0xbfb8aa3b, v10
	v_exp_f32_e32 v10, v10
	v_add_f32_e32 v11, 1.0, v11
	v_rcp_f32_e32 v11, v11
	v_add_f32_e32 v10, 1.0, v10
	v_rcp_f32_e32 v10, v10
	s_waitcnt lgkmcnt(0)
	v_lshlrev_b32_e32 v9, 16, v98
	v_mul_f32_e32 v9, v11, v9
	v_add_f32_e32 v11, v192, v25
	v_mul_f32_e32 v11, 0xbfb8aa3b, v11
	v_exp_f32_e32 v11, v11
	v_mul_f32_e32 v10, v194, v10
	v_exp_f32_e32 v200, v10
	v_mul_f32_e32 v10, 0x3fb17218, v10
	v_fmamk_f32 v12, v10, 0x3c088888, v186
	v_fmaak_f32 v12, v10, v12, 0x3e2aaaab
	v_add_f32_e32 v11, 1.0, v11
	v_fma_f32 v12, v10, v12, 0.5
	v_rcp_f32_e32 v11, v11
	v_fma_f32 v12, v10, v12, 1.0
	v_mul_f32_e32 v12, v10, v12
	v_fma_f32 v13, v200, v200, -1.0
	v_cmp_lt_f32_e32 vcc, s76, v10
	v_mul_f32_e32 v11, v194, v11
	v_exp_f32_e32 v207, v11
	v_cndmask_b32_e32 v10, v13, v12, vcc
	v_add_f32_e32 v12, v191, v41
	v_mul_f32_e32 v12, 0xbfb8aa3b, v12
	v_mul_f32_e32 v11, 0x3fb17218, v11
	v_exp_f32_e32 v12, v12
	v_fmamk_f32 v14, v11, 0x3c088888, v186
	v_fmaak_f32 v14, v11, v14, 0x3e2aaaab
	v_fma_f32 v14, v11, v14, 0.5
	v_fma_f32 v14, v11, v14, 1.0
	v_sqrt_f32_e64 v10, -v10
	v_add_f32_e32 v12, 1.0, v12
	v_mul_f32_e32 v14, v11, v14
	v_fma_f32 v15, v207, v207, -1.0
	v_cmp_lt_f32_e32 vcc, s76, v11
	v_rcp_f32_e32 v12, v12
	v_mul_f32_e32 v222, v10, v9
	v_cndmask_b32_e32 v11, v15, v14, vcc
	v_sqrt_f32_e64 v11, -v11
	s_waitcnt lgkmcnt(0)
	v_lshlrev_b32_e32 v9, 16, v99
	v_mul_f32_e32 v9, v12, v9
	v_add_f32_e32 v10, v192, v26
	v_mul_f32_e32 v221, v11, v9
	v_add_f32_e32 v11, v191, v42
	v_mul_f32_e32 v11, 0xbfb8aa3b, v11
	v_exp_f32_e32 v11, v11
	v_mul_f32_e32 v10, 0xbfb8aa3b, v10
	v_exp_f32_e32 v10, v10
	v_add_f32_e32 v11, 1.0, v11
	v_rcp_f32_e32 v11, v11
	v_add_f32_e32 v10, 1.0, v10
	v_rcp_f32_e32 v10, v10
	s_waitcnt lgkmcnt(0)
	v_lshlrev_b32_e32 v9, 16, v100
	v_mul_f32_e32 v9, v11, v9
	v_add_f32_e32 v11, v192, v27
	v_mul_f32_e32 v11, 0xbfb8aa3b, v11
	v_exp_f32_e32 v11, v11
	v_mul_f32_e32 v10, v194, v10
	v_exp_f32_e32 v203, v10
	v_mul_f32_e32 v10, 0x3fb17218, v10
	v_fmamk_f32 v12, v10, 0x3c088888, v186
	v_fmaak_f32 v12, v10, v12, 0x3e2aaaab
	v_add_f32_e32 v11, 1.0, v11
	v_fma_f32 v12, v10, v12, 0.5
	v_rcp_f32_e32 v11, v11
	v_fma_f32 v12, v10, v12, 1.0
	v_mul_f32_e32 v12, v10, v12
	v_fma_f32 v13, v203, v203, -1.0
	v_cmp_lt_f32_e32 vcc, s76, v10
	v_mul_f32_e32 v11, v194, v11
	v_exp_f32_e32 v210, v11
	v_cndmask_b32_e32 v10, v13, v12, vcc
	v_add_f32_e32 v12, v191, v43
	v_mul_f32_e32 v12, 0xbfb8aa3b, v12
	v_mul_f32_e32 v11, 0x3fb17218, v11
	v_exp_f32_e32 v12, v12
	v_fmamk_f32 v14, v11, 0x3c088888, v186
	v_fmaak_f32 v14, v11, v14, 0x3e2aaaab
	v_fma_f32 v14, v11, v14, 0.5
	v_fma_f32 v14, v11, v14, 1.0
	v_sqrt_f32_e64 v10, -v10
	v_add_f32_e32 v12, 1.0, v12
	v_mul_f32_e32 v14, v11, v14
	v_fma_f32 v15, v210, v210, -1.0
	v_cmp_lt_f32_e32 vcc, s76, v11
	v_rcp_f32_e32 v12, v12
	v_mul_f32_e32 v216, v10, v9
	v_cndmask_b32_e32 v11, v15, v14, vcc
	v_sqrt_f32_e64 v11, -v11
	s_waitcnt lgkmcnt(0)
	v_lshlrev_b32_e32 v9, 16, v101
	v_mul_f32_e32 v9, v12, v9
	v_add_f32_e32 v10, v192, v28
	v_mul_f32_e32 v215, v11, v9
	v_add_f32_e32 v11, v191, v44
	v_mul_f32_e32 v11, 0xbfb8aa3b, v11
	v_exp_f32_e32 v11, v11
	v_mul_f32_e32 v10, 0xbfb8aa3b, v10
	v_exp_f32_e32 v10, v10
	v_add_f32_e32 v11, 1.0, v11
	v_rcp_f32_e32 v11, v11
	v_add_f32_e32 v10, 1.0, v10
	v_rcp_f32_e32 v10, v10
	s_waitcnt lgkmcnt(0)
; __device__ __forceinline__ float bf2f(bf16_t b) { return __uint_as_float(((unsigned)b) << 16); }
; __device__ __forceinline__ float fast_sigmoid(float x) { return __builtin_amdgcn_rcpf(1.0f + __builtin_amdgcn_exp2f(-1.4426950408889634f * x)); }
; template <int DIR>
; __device__ __forceinline__ void scan_dir(PP p, const bf16_t* xs, const ScanW& w, ScanW& wn, int ndir, int nct, bool do_next, int n, int ct, int l31, int hl, int id, int rowbase, bool latent, float (&hf)[2][16]) {
;     ...
; #pragma unroll
;         for (int i = 0; i < 16; ++i) {
;             const int token = 32 * rt + 8 * (i >> 2) + 4 * hl + (i & 3);
;             const float xv = bf2f(xs[token * XS + ch]);
;             const float rr = fast_sigmoid(ga[i] + ba), ii = fast_sigmoid(gi[i] + bi);
;             const float la2 = rr * sp8l2;
;             const float av = __builtin_amdgcn_exp2f(la2);
;             const float t2 = la2 * 1.3862943611f;
;             float em1p = t2 * (1.0f + t2 * (0.5f + t2 * (0.16666667f + t2 * (0.041666668f + t2 * 0.0083333333f)))), em1e = __builtin_fmaf(av, av, -1.0f);
;             asm volatile("" : "+v"(em1p), "+v"(em1e));
;             const float em1 = (t2 > -0.1f) ? em1p : em1e;
;             a[rt][i] = av; u[rt][i] = __builtin_amdgcn_sqrtf(-em1) * (ii * xv);
;         }
;     }
;     float Ao[8], Ho[8], Ap[8], Hp[8];
; #pragma unroll
;     for (int k = 0; k < 8; ++k) {
;         const int rt = k >> 2, g = k & 3;
;         float H = 0.f, A = 1.f;
; #pragma unroll
;         for (int jj = 0; jj < 4; ++jj) { const int j = DIR ? 3 - jj : jj; const float av = a[rt][4 * g + j]; H = av * H + u[rt][4 * g + j]; A *= av; }
;         Ao[k] = A; Ho[k] = H; Ap[k] = __shfl_xor(A, 32); Hp[k] = __shfl_xor(H, 32);
	v_lshlrev_b32_e32 v9, 16, v102
	v_mul_f32_e32 v9, v11, v9
	v_add_f32_e32 v11, v192, v29
	v_mul_f32_e32 v11, 0xbfb8aa3b, v11
	v_exp_f32_e32 v11, v11
	v_mul_f32_e32 v10, v194, v10
	v_exp_f32_e32 v208, v10
	v_mul_f32_e32 v10, 0x3fb17218, v10
	v_fmamk_f32 v12, v10, 0x3c088888, v186
	v_fmaak_f32 v12, v10, v12, 0x3e2aaaab
	v_add_f32_e32 v11, 1.0, v11
	v_fma_f32 v12, v10, v12, 0.5
	v_rcp_f32_e32 v11, v11
	v_fma_f32 v12, v10, v12, 1.0
	v_mul_f32_e32 v12, v10, v12
	v_fma_f32 v13, v208, v208, -1.0
	v_cmp_lt_f32_e32 vcc, s76, v10
	v_mul_f32_e32 v11, v194, v11
	v_exp_f32_e32 v218, v11
	v_cndmask_b32_e32 v10, v13, v12, vcc
	v_add_f32_e32 v12, v191, v45
	v_mul_f32_e32 v12, 0xbfb8aa3b, v12
	v_mul_f32_e32 v11, 0x3fb17218, v11
	v_exp_f32_e32 v12, v12
	v_fmamk_f32 v14, v11, 0x3c088888, v186
	v_fmaak_f32 v14, v11, v14, 0x3e2aaaab
	v_fma_f32 v14, v11, v14, 0.5
	v_fma_f32 v14, v11, v14, 1.0
	v_sqrt_f32_e64 v10, -v10
	v_add_f32_e32 v12, 1.0, v12
	v_mul_f32_e32 v14, v11, v14
	v_fma_f32 v15, v218, v218, -1.0
	v_cmp_lt_f32_e32 vcc, s76, v11
	v_rcp_f32_e32 v12, v12
	v_mul_f32_e32 v227, v10, v9
	v_cndmask_b32_e32 v11, v15, v14, vcc
	v_sqrt_f32_e64 v11, -v11
	s_waitcnt lgkmcnt(0)
	v_lshlrev_b32_e32 v9, 16, v103
	v_mul_f32_e32 v9, v12, v9
	v_add_f32_e32 v10, v192, v30
	v_mul_f32_e32 v226, v11, v9
	v_add_f32_e32 v11, v191, v46
	v_mul_f32_e32 v11, 0xbfb8aa3b, v11
	v_exp_f32_e32 v11, v11
	v_mul_f32_e32 v10, 0xbfb8aa3b, v10
	v_exp_f32_e32 v10, v10
	v_add_f32_e32 v11, 1.0, v11
	v_rcp_f32_e32 v11, v11
	v_add_f32_e32 v10, 1.0, v10
	v_rcp_f32_e32 v10, v10
	s_waitcnt lgkmcnt(0)
	v_lshlrev_b32_e32 v9, 16, v104
	v_mul_f32_e32 v9, v11, v9
	v_add_f32_e32 v11, v192, v31
	v_mul_f32_e32 v11, 0xbfb8aa3b, v11
	v_exp_f32_e32 v11, v11
	v_mul_f32_e32 v10, v194, v10
	v_exp_f32_e32 v213, v10
	v_mul_f32_e32 v10, 0x3fb17218, v10
	v_fmamk_f32 v12, v10, 0x3c088888, v186
	v_fmaak_f32 v12, v10, v12, 0x3e2aaaab
	v_add_f32_e32 v11, 1.0, v11
	v_fma_f32 v12, v10, v12, 0.5
	v_rcp_f32_e32 v11, v11
	v_fma_f32 v12, v10, v12, 1.0
	v_mul_f32_e32 v12, v10, v12
	v_fma_f32 v13, v213, v213, -1.0
	v_cmp_lt_f32_e32 vcc, s76, v10
	v_mul_f32_e32 v11, v194, v11
	v_exp_f32_e32 v220, v11
	v_cndmask_b32_e32 v10, v13, v12, vcc
	v_add_f32_e32 v12, v191, v47
	v_mul_f32_e32 v12, 0xbfb8aa3b, v12
	v_mul_f32_e32 v11, 0x3fb17218, v11
	v_exp_f32_e32 v12, v12
	v_fmamk_f32 v14, v11, 0x3c088888, v186
	v_fmaak_f32 v14, v11, v14, 0x3e2aaaab
	v_fma_f32 v14, v11, v14, 0.5
	v_fma_f32 v14, v11, v14, 1.0
	v_sqrt_f32_e64 v10, -v10
	v_add_f32_e32 v12, 1.0, v12
	v_mul_f32_e32 v14, v11, v14
	v_fma_f32 v15, v220, v220, -1.0
	v_cmp_lt_f32_e32 vcc, s76, v11
	v_rcp_f32_e32 v12, v12
	v_mul_f32_e32 v224, v10, v9
	v_cndmask_b32_e32 v11, v15, v14, vcc
	v_sqrt_f32_e64 v11, -v11
	s_waitcnt lgkmcnt(0)
	v_lshlrev_b32_e32 v9, 16, v105
	v_mul_f32_e32 v9, v12, v9
	v_add_f32_e32 v10, v192, v32
	v_mul_f32_e32 v223, v11, v9
	v_add_f32_e32 v11, v191, v48
	v_mul_f32_e32 v11, 0xbfb8aa3b, v11
	v_exp_f32_e32 v11, v11
	v_mul_f32_e32 v10, 0xbfb8aa3b, v10
	v_exp_f32_e32 v10, v10
	v_add_f32_e32 v11, 1.0, v11
	v_rcp_f32_e32 v11, v11
	v_add_f32_e32 v10, 1.0, v10
	v_rcp_f32_e32 v10, v10
	s_waitcnt lgkmcnt(0)
	v_lshlrev_b32_e32 v9, 16, v106
	v_mul_f32_e32 v9, v11, v9
	v_add_f32_e32 v11, v192, v33
	v_mul_f32_e32 v11, 0xbfb8aa3b, v11
	v_exp_f32_e32 v11, v11
	v_mul_f32_e32 v10, v194, v10
	v_exp_f32_e32 v219, v10
	v_mul_f32_e32 v10, 0x3fb17218, v10
	v_fmamk_f32 v12, v10, 0x3c088888, v186
	v_fmaak_f32 v12, v10, v12, 0x3e2aaaab
	v_add_f32_e32 v11, 1.0, v11
	v_fma_f32 v12, v10, v12, 0.5
	v_rcp_f32_e32 v11, v11
	v_fma_f32 v12, v10, v12, 1.0
	v_mul_f32_e32 v12, v10, v12
	v_fma_f32 v13, v219, v219, -1.0
	v_cmp_lt_f32_e32 vcc, s76, v10
	v_mul_f32_e32 v11, v194, v11
	v_exp_f32_e32 v225, v11
	v_cndmask_b32_e32 v10, v13, v12, vcc
	v_add_f32_e32 v12, v191, v49
	v_mul_f32_e32 v12, 0xbfb8aa3b, v12
	v_mul_f32_e32 v11, 0x3fb17218, v11
	v_exp_f32_e32 v12, v12
	v_fmamk_f32 v13, v11, 0x3c088888, v186
	v_fmaak_f32 v13, v11, v13, 0x3e2aaaab
	v_fma_f32 v13, v11, v13, 0.5
	ds_read_u16 v0, v0 offset:61360
	v_fma_f32 v13, v11, v13, 1.0
	v_add_f32_e32 v12, 1.0, v12
	v_mul_f32_e32 v13, v11, v13
	v_fma_f32 v14, v225, v225, -1.0
	v_cmp_lt_f32_e32 vcc, s76, v11
	v_sqrt_f32_e64 v10, -v10
	v_rcp_f32_e32 v12, v12
	s_waitcnt lgkmcnt(0)
	v_lshlrev_b32_e32 v0, 16, v0
	v_cndmask_b32_e32 v11, v14, v13, vcc
	v_sqrt_f32_e64 v11, -v11
	v_mul_f32_e32 v229, v10, v9
	v_mul_f32_e32 v0, v12, v0
	v_and_b32_e32 v9, 64, v188
	v_mul_f32_e32 v228, v11, v0
	v_xor_b32_e32 v0, 32, v188
	v_add_u32_e32 v9, 64, v9
	v_cmp_lt_i32_e32 vcc, v0, v9
	v_fma_f32 v9, 0, v50, v2
	v_fma_f32 v9, v52, v9, v3
	v_fma_f32 v9, v51, v9, v4
	v_fma_f32 v34, v54, v9, v5
	v_fma_f32 v9, 0, v53, v6
	v_fma_f32 v9, v55, v9, v7
	v_fma_f32 v9, v67, v9, v8
	v_fma_f32 v255, v69, v9, v76
	v_fma_f32 v9, 0, v68, v74
	v_fma_f32 v9, v71, v9, v73
	v_mul_f32_e32 v10, v50, v52
	v_fma_f32 v9, v70, v9, v209
	v_mul_f32_e32 v10, v51, v10
	v_fma_f32 v251, v75, v9, v217
	v_fma_f32 v9, 0, v72, v197
	v_mul_f32_e32 v35, v54, v10
	v_mul_f32_e32 v10, v53, v55
	v_fma_f32 v9, v78, v9, v199
	v_mul_f32_e32 v10, v67, v10
	v_fma_f32 v9, v77, v9, v204
	v_mul_f32_e32 v154, v69, v10
	v_mul_f32_e32 v10, v68, v71
	v_fma_f32 v247, v79, v9, v202
	v_fma_f32 v9, 0, v80, v196
	v_mul_f32_e32 v10, v70, v10
	v_fma_f32 v9, v146, v9, v195
	v_mul_f32_e32 v253, v75, v10
	v_mul_f32_e32 v10, v72, v78
	v_fma_f32 v9, v81, v9, v214
	v_mul_f32_e32 v10, v77, v10
	v_fma_f32 v243, v198, v9, v211
	v_fma_f32 v9, 0, v147, v206
	v_mul_f32_e32 v249, v79, v10
	v_mul_f32_e32 v10, v80, v146
	v_fma_f32 v9, v201, v9, v205
	v_mul_f32_e32 v10, v81, v10
	v_fma_f32 v9, v200, v9, v222
	v_mul_f32_e32 v245, v198, v10
	v_mul_f32_e32 v10, v147, v201
	v_fma_f32 v239, v207, v9, v221
	v_fma_f32 v9, 0, v203, v216
	v_mul_f32_e32 v10, v200, v10
	v_fma_f32 v9, v210, v9, v215
	v_mul_f32_e32 v241, v207, v10
	v_mul_f32_e32 v10, v203, v210
	v_fma_f32 v9, v208, v9, v227
	v_mul_f32_e32 v10, v208, v10
	v_fma_f32 v234, v218, v9, v226
	v_fma_f32 v9, 0, v213, v224
	v_mul_f32_e32 v236, v218, v10
	v_fma_f32 v9, v220, v9, v223
	v_mul_f32_e32 v10, v213, v220
	v_cndmask_b32_e32 v0, v188, v0, vcc
	v_fma_f32 v9, v219, v9, v229
	v_mul_f32_e32 v10, v219, v10
	v_lshlrev_b32_e32 v0, 2, v0
	v_fma_f32 v230, v225, v9, v228
	v_mul_f32_e32 v231, v225, v10
	ds_bpermute_b32 v36, v0, v35
	ds_bpermute_b32 v37, v0, v34
	ds_bpermute_b32 v155, v0, v154
	ds_bpermute_b32 v212, v0, v255
	ds_bpermute_b32 v254, v0, v253
	ds_bpermute_b32 v252, v0, v251
	ds_bpermute_b32 v250, v0, v249
	ds_bpermute_b32 v248, v0, v247
	ds_bpermute_b32 v246, v0, v245
	ds_bpermute_b32 v244, v0, v243
	ds_bpermute_b32 v242, v0, v241
	ds_bpermute_b32 v240, v0, v239
	ds_bpermute_b32 v237, v0, v236
	ds_bpermute_b32 v235, v0, v234
	ds_bpermute_b32 v232, v0, v231
	ds_bpermute_b32 v233, v0, v230
	v_cndmask_b32_e64 v0, 0, 1, s[22:23]
	v_cmp_ne_u32_e64 s[4:5], 1, v0
	s_andn2_b64 vcc, exec, s[22:23]
	s_cbranch_vccnz .LBB0_380
; __device__ __forceinline__ void scan_loadw(PP p, int dir, int n, int ct, int l31, int hl, ScanW& w) {
;     unsigned chv = (unsigned)(32 * ct + l31); asm volatile("" : "+v"(chv));
;     const unsigned ch = (unsigned)(dir * 512 + 64 * n) + chv;
;     w.ba = p->lru_b_a[ch]; w.bi = p->lru_b_i[ch];
;     w.sp8l2 = ((const float*)(p->ws + WS_SP8))[ch] * 1.4426950408889634f;
;     const bf16_t* wa_b = (const bf16_t*)(p->ws + WS_LRU) + (size_t)((dir * 2 + 0) * 8 + n) * 4096;
;     const bf16_t* wi_b = (const bf16_t*)(p->ws + WS_LRU) + (size_t)((dir * 2 + 1) * 8 + n) * 4096;
;     const unsigned lo = chv * 64u + 8u * (unsigned)hl;
; #pragma unroll
;     for (int st = 0; st < 4; ++st) { w.wfa[st] = *(const bf16x8*)(wa_b + lo + 16 * st); w.wfi[st] = *(const bf16x8*)(wi_b + lo + 16 * st); }
; }
	v_or_b32_e32 v9, s48, v148
	s_load_dwordx2 s[48:49], s[8:9], 0x58
	s_load_dwordx2 s[82:83], s[8:9], 0x68
	v_add_u32_e32 v0, s50, v9
	v_lshlrev_b64 v[10:11], 2, v[0:1]
	v_lshl_or_b32 v0, v9, 6, v149
	s_waitcnt lgkmcnt(0)
	v_lshl_add_u64 v[12:13], s[48:49], 0, v[10:11]
	global_load_dword v189, v[12:13], off
	v_lshl_add_u64 v[12:13], s[82:83], 0, v[10:11]
	global_load_dword v190, v[12:13], off
	v_lshl_add_u64 v[10:11], s[12:13], 0, v[10:11]
	v_lshlrev_b64 v[12:13], 1, v[0:1]
	v_lshl_add_u64 v[14:15], s[20:21], 0, v[12:13]
	v_lshl_add_u64 v[12:13], s[16:17], 0, v[12:13]
	global_load_dword v144, v[10:11], off
	global_load_dwordx4 v[82:85], v[14:15], off
	global_load_dwordx4 v[86:89], v[14:15], off offset:32
	global_load_dwordx4 v[90:93], v[14:15], off offset:64
	global_load_dwordx4 v[94:97], v[12:13], off offset:32
	global_load_dwordx4 v[102:105], v[12:13], off offset:64
	global_load_dwordx4 v[98:101], v[12:13], off
	global_load_dwordx4 v[106:109], v[14:15], off offset:96
	global_load_dwordx4 v[110:113], v[12:13], off offset:96
